# GU epilogue math rewritten: 8 elements per row group interleaved, in place, no pairing moves or wait-state nops (same f32 ops)
# speedup vs baseline: 1.0210x; 1.0057x over previous
; __device__ __forceinline__ unsigned cvt_pk_bf16(float lo, float hi) { unsigned r; asm volatile("v_cvt_pk_bf16_f32 %0, %1, %2" : "=v"(r) : "v"(lo), "v"(hi)); return r; }
; #define LAS __attribute__((address_space(3)))
; __device__ __forceinline__ float fast_sigmoid(float v) { return __builtin_amdgcn_rcpf(1.0f + __expf(-v)); }
;     __device__ __forceinline__ void operator()(const f32x4 (&acc)[2][2][4][2], const Unit& u, int wr, int wc, int fr, int fq) const {
;         const int row0 = u.pm * 256 + wr * 64 + fr, col0 = u.pn * 128 + wc * 32 + 8 * fq;
;         float sc[2][4];
;         { const LAS float* t_ = rs + ui * 256 + wr * 64 + fr;
; #pragma unroll
;           for (int ai = 0; ai < 2; ++ai)
; #pragma unroll
;               for (int m = 0; m < 4; ++m) sc[ai][m] = t_[ai * 128 + m * 16];
;           ++ui; }
; #pragma unroll
;         for (int ai = 0; ai < 2; ++ai)
; #pragma unroll
;             for (int m = 0; m < 4; ++m) {
;                 const int row = row0 + ai * 128 + m * 16; const float s = sc[ai][m];
;                 float a[8];
; #pragma unroll
;                 for (int n = 0; n < 2; ++n) { const f32x4 g = acc[ai][0][m][n] * s, up = acc[ai][1][m][n] * s;
; #pragma unroll
;                     for (int j = 0; j < 4; ++j) a[4 * n + j] = g[j] * fast_sigmoid(g[j]) * up[j]; }
;                 u32x4 w; w.x = cvt_pk_bf16(a[0], a[1]); w.y = cvt_pk_bf16(a[2], a[3]); w.z = cvt_pk_bf16(a[4], a[5]); w.w = cvt_pk_bf16(a[6], a[7]);
;                 *(u32x4*)(act + (size_t)row * FF + col0) = w;
;             }
.LBB0_221:
	v_lshl_add_u32 v148, s51, 10, v155
	ds_read2_b32 v[162:163], v148 offset1:16
	ds_read2_b32 v[152:153], v148 offset0:32 offset1:48
	ds_read2_b32 v[150:151], v148 offset0:128 offset1:144
	ds_read2_b32 v[148:149], v148 offset0:160 offset1:176
	s_waitcnt lgkmcnt(0)
	v_mul_f32_e32 v124, v124, v162
	v_mul_f32_e32 v125, v125, v162
	v_mul_f32_e32 v126, v126, v162
	v_mul_f32_e32 v127, v127, v162
	v_mul_f32_e32 v116, v116, v162
	v_mul_f32_e32 v117, v117, v162
	v_mul_f32_e32 v118, v118, v162
	v_mul_f32_e32 v119, v119, v162
	v_mul_f32_e32 v120, v120, v162
	v_mul_f32_e32 v121, v121, v162
	v_mul_f32_e32 v122, v122, v162
	v_mul_f32_e32 v123, v123, v162
	v_mul_f32_e32 v112, v112, v162
	v_mul_f32_e32 v113, v113, v162
	v_mul_f32_e32 v114, v114, v162
	v_mul_f32_e32 v115, v115, v162
	v_mul_f32_e32 v170, 0xbfb8aa3b, v124
	v_mul_f32_e32 v171, 0xbfb8aa3b, v125
	v_mul_f32_e32 v172, 0xbfb8aa3b, v126
	v_mul_f32_e32 v173, 0xbfb8aa3b, v127
	v_mul_f32_e32 v174, 0xbfb8aa3b, v116
	v_mul_f32_e32 v175, 0xbfb8aa3b, v117
	v_mul_f32_e32 v176, 0xbfb8aa3b, v118
	v_mul_f32_e32 v177, 0xbfb8aa3b, v119
	v_exp_f32_e32 v170, v170
	v_exp_f32_e32 v171, v171
	v_exp_f32_e32 v172, v172
	v_exp_f32_e32 v173, v173
	v_exp_f32_e32 v174, v174
	v_exp_f32_e32 v175, v175
	v_exp_f32_e32 v176, v176
	v_exp_f32_e32 v177, v177
	v_add_f32_e32 v170, 1.0, v170
	v_add_f32_e32 v171, 1.0, v171
	v_add_f32_e32 v172, 1.0, v172
	v_add_f32_e32 v173, 1.0, v173
	v_add_f32_e32 v174, 1.0, v174
	v_add_f32_e32 v175, 1.0, v175
	v_add_f32_e32 v176, 1.0, v176
	v_add_f32_e32 v177, 1.0, v177
	v_rcp_f32_e32 v170, v170
	v_rcp_f32_e32 v171, v171
	v_rcp_f32_e32 v172, v172
	v_rcp_f32_e32 v173, v173
	v_rcp_f32_e32 v174, v174
	v_rcp_f32_e32 v175, v175
	v_rcp_f32_e32 v176, v176
	v_rcp_f32_e32 v177, v177
	v_mul_f32_e32 v124, v124, v170
	v_mul_f32_e32 v125, v125, v171
	v_mul_f32_e32 v126, v126, v172
	v_mul_f32_e32 v127, v127, v173
	v_mul_f32_e32 v116, v116, v174
	v_mul_f32_e32 v117, v117, v175
	v_mul_f32_e32 v118, v118, v176
	v_mul_f32_e32 v119, v119, v177
	v_mul_f32_e32 v170, v120, v124
	v_mul_f32_e32 v171, v121, v125
	v_mul_f32_e32 v172, v122, v126
	v_mul_f32_e32 v173, v123, v127
	v_mul_f32_e32 v174, v112, v116
	v_mul_f32_e32 v175, v113, v117
	v_mul_f32_e32 v176, v114, v118
	v_mul_f32_e32 v177, v115, v119
	v_cvt_pk_bf16_f32 v116, v170, v171
	v_cvt_pk_bf16_f32 v117, v172, v173
	v_cvt_pk_bf16_f32 v118, v174, v175
	v_cvt_pk_bf16_f32 v119, v176, v177
	v_lshl_or_b32 v166, s77, 7, v156
	v_lshl_add_u32 v161, s50, 8, v131
	v_ashrrev_i32_e32 v167, 31, v166
	s_mov_b64 s[50:51], -1
	s_andn2_b64 vcc, exec, s[42:43]
	v_mov_b64_e32 v[112:113], s[24:25]
	v_mad_i64_i32 v[120:121], s[6:7], v161, s75, v[112:113]
	v_lshlrev_b64 v[114:115], 1, v[166:167]
	v_lshl_add_u64 v[120:121], v[120:121], 0, v[114:115]
	global_store_dwordx4 v[120:121], v[116:119], off
	v_mul_f32_e32 v108, v108, v163
	v_mul_f32_e32 v109, v109, v163
	v_mul_f32_e32 v110, v110, v163
	v_mul_f32_e32 v111, v111, v163
	v_mul_f32_e32 v100, v100, v163
	v_mul_f32_e32 v101, v101, v163
	v_mul_f32_e32 v102, v102, v163
	v_mul_f32_e32 v103, v103, v163
	v_mul_f32_e32 v104, v104, v163
	v_mul_f32_e32 v105, v105, v163
	v_mul_f32_e32 v106, v106, v163
	v_mul_f32_e32 v107, v107, v163
	v_mul_f32_e32 v96, v96, v163
	v_mul_f32_e32 v97, v97, v163
	v_mul_f32_e32 v98, v98, v163
	v_mul_f32_e32 v99, v99, v163
	v_mul_f32_e32 v170, 0xbfb8aa3b, v108
	v_mul_f32_e32 v171, 0xbfb8aa3b, v109
	v_mul_f32_e32 v172, 0xbfb8aa3b, v110
	v_mul_f32_e32 v173, 0xbfb8aa3b, v111
	v_mul_f32_e32 v174, 0xbfb8aa3b, v100
	v_mul_f32_e32 v175, 0xbfb8aa3b, v101
	v_mul_f32_e32 v176, 0xbfb8aa3b, v102
	v_mul_f32_e32 v177, 0xbfb8aa3b, v103
	v_exp_f32_e32 v170, v170
	v_exp_f32_e32 v171, v171
	v_exp_f32_e32 v172, v172
	v_exp_f32_e32 v173, v173
	v_exp_f32_e32 v174, v174
	v_exp_f32_e32 v175, v175
	v_exp_f32_e32 v176, v176
	v_exp_f32_e32 v177, v177
	v_add_f32_e32 v170, 1.0, v170
	v_add_f32_e32 v171, 1.0, v171
	v_add_f32_e32 v172, 1.0, v172
	v_add_f32_e32 v173, 1.0, v173
	v_add_f32_e32 v174, 1.0, v174
	v_add_f32_e32 v175, 1.0, v175
	v_add_f32_e32 v176, 1.0, v176
	v_add_f32_e32 v177, 1.0, v177
	v_rcp_f32_e32 v170, v170
	v_rcp_f32_e32 v171, v171
	v_rcp_f32_e32 v172, v172
	v_rcp_f32_e32 v173, v173
	v_rcp_f32_e32 v174, v174
	v_rcp_f32_e32 v175, v175
	v_rcp_f32_e32 v176, v176
	v_rcp_f32_e32 v177, v177
	v_mul_f32_e32 v108, v108, v170
	v_mul_f32_e32 v109, v109, v171
	v_mul_f32_e32 v110, v110, v172
	v_mul_f32_e32 v111, v111, v173
	v_mul_f32_e32 v100, v100, v174
	v_mul_f32_e32 v101, v101, v175
	v_mul_f32_e32 v102, v102, v176
	v_mul_f32_e32 v103, v103, v177
	v_mul_f32_e32 v170, v104, v108
	v_mul_f32_e32 v171, v105, v109
	v_mul_f32_e32 v172, v106, v110
	v_mul_f32_e32 v173, v107, v111
	v_mul_f32_e32 v174, v96, v100
	v_mul_f32_e32 v175, v97, v101
	v_mul_f32_e32 v176, v98, v102
	v_mul_f32_e32 v177, v99, v103
	v_cvt_pk_bf16_f32 v96, v170, v171
	v_cvt_pk_bf16_f32 v97, v172, v173
	v_cvt_pk_bf16_f32 v98, v174, v175
	v_cvt_pk_bf16_f32 v99, v176, v177
	v_or_b32_e32 v102, 16, v161
	v_mad_i64_i32 v[100:101], s[6:7], v102, s75, v[112:113]
	v_lshl_add_u64 v[100:101], v[100:101], 0, v[114:115]
	global_store_dwordx4 v[100:101], v[96:99], off
	v_mul_f32_e32 v92, v92, v152
	v_mul_f32_e32 v93, v93, v152
	v_mul_f32_e32 v94, v94, v152
	v_mul_f32_e32 v95, v95, v152
	v_mul_f32_e32 v84, v84, v152
	v_mul_f32_e32 v85, v85, v152
	v_mul_f32_e32 v86, v86, v152
	v_mul_f32_e32 v87, v87, v152
	v_mul_f32_e32 v88, v88, v152
	v_mul_f32_e32 v89, v89, v152
	v_mul_f32_e32 v90, v90, v152
	v_mul_f32_e32 v91, v91, v152
	v_mul_f32_e32 v80, v80, v152
	v_mul_f32_e32 v81, v81, v152
	v_mul_f32_e32 v82, v82, v152
	v_mul_f32_e32 v83, v83, v152
	v_mul_f32_e32 v170, 0xbfb8aa3b, v92
; __device__ __forceinline__ unsigned cvt_pk_bf16(float lo, float hi) { unsigned r; asm volatile("v_cvt_pk_bf16_f32 %0, %1, %2" : "=v"(r) : "v"(lo), "v"(hi)); return r; }
; __device__ __forceinline__ float fast_sigmoid(float v) { return __builtin_amdgcn_rcpf(1.0f + __expf(-v)); }
;     __device__ __forceinline__ void operator()(const f32x4 (&acc)[2][2][4][2], const Unit& u, int wr, int wc, int fr, int fq) const {
;     ...
;         for (int ai = 0; ai < 2; ++ai)
; #pragma unroll
;             for (int m = 0; m < 4; ++m) {
;                 const int row = row0 + ai * 128 + m * 16; const float s = sc[ai][m];
;                 float a[8];
; #pragma unroll
;                 for (int n = 0; n < 2; ++n) { const f32x4 g = acc[ai][0][m][n] * s, up = acc[ai][1][m][n] * s;
; #pragma unroll
;                     for (int j = 0; j < 4; ++j) a[4 * n + j] = g[j] * fast_sigmoid(g[j]) * up[j]; }
;                 u32x4 w; w.x = cvt_pk_bf16(a[0], a[1]); w.y = cvt_pk_bf16(a[2], a[3]); w.z = cvt_pk_bf16(a[4], a[5]); w.w = cvt_pk_bf16(a[6], a[7]);
;                 *(u32x4*)(act + (size_t)row * FF + col0) = w;
;             }
	v_mul_f32_e32 v171, 0xbfb8aa3b, v93
	v_mul_f32_e32 v172, 0xbfb8aa3b, v94
	v_mul_f32_e32 v173, 0xbfb8aa3b, v95
	v_mul_f32_e32 v174, 0xbfb8aa3b, v84
	v_mul_f32_e32 v175, 0xbfb8aa3b, v85
	v_mul_f32_e32 v176, 0xbfb8aa3b, v86
	v_mul_f32_e32 v177, 0xbfb8aa3b, v87
	v_exp_f32_e32 v170, v170
	v_exp_f32_e32 v171, v171
	v_exp_f32_e32 v172, v172
	v_exp_f32_e32 v173, v173
	v_exp_f32_e32 v174, v174
	v_exp_f32_e32 v175, v175
	v_exp_f32_e32 v176, v176
	v_exp_f32_e32 v177, v177
	v_add_f32_e32 v170, 1.0, v170
	v_add_f32_e32 v171, 1.0, v171
	v_add_f32_e32 v172, 1.0, v172
	v_add_f32_e32 v173, 1.0, v173
	v_add_f32_e32 v174, 1.0, v174
	v_add_f32_e32 v175, 1.0, v175
	v_add_f32_e32 v176, 1.0, v176
	v_add_f32_e32 v177, 1.0, v177
	v_rcp_f32_e32 v170, v170
	v_rcp_f32_e32 v171, v171
	v_rcp_f32_e32 v172, v172
	v_rcp_f32_e32 v173, v173
	v_rcp_f32_e32 v174, v174
	v_rcp_f32_e32 v175, v175
	v_rcp_f32_e32 v176, v176
	v_rcp_f32_e32 v177, v177
	v_mul_f32_e32 v92, v92, v170
	v_mul_f32_e32 v93, v93, v171
	v_mul_f32_e32 v94, v94, v172
	v_mul_f32_e32 v95, v95, v173
	v_mul_f32_e32 v84, v84, v174
	v_mul_f32_e32 v85, v85, v175
	v_mul_f32_e32 v86, v86, v176
	v_mul_f32_e32 v87, v87, v177
	v_mul_f32_e32 v170, v88, v92
	v_mul_f32_e32 v171, v89, v93
	v_mul_f32_e32 v172, v90, v94
	v_mul_f32_e32 v173, v91, v95
	v_mul_f32_e32 v174, v80, v84
	v_mul_f32_e32 v175, v81, v85
	v_mul_f32_e32 v176, v82, v86
	v_mul_f32_e32 v177, v83, v87
	v_cvt_pk_bf16_f32 v80, v170, v171
	v_cvt_pk_bf16_f32 v81, v172, v173
	v_cvt_pk_bf16_f32 v82, v174, v175
	v_cvt_pk_bf16_f32 v83, v176, v177
	v_or_b32_e32 v86, 32, v161
	v_mad_i64_i32 v[84:85], s[6:7], v86, s75, v[112:113]
	v_lshl_add_u64 v[84:85], v[84:85], 0, v[114:115]
	global_store_dwordx4 v[84:85], v[80:83], off
	v_mul_f32_e32 v76, v76, v153
	v_mul_f32_e32 v77, v77, v153
	v_mul_f32_e32 v78, v78, v153
	v_mul_f32_e32 v79, v79, v153
	v_mul_f32_e32 v68, v68, v153
	v_mul_f32_e32 v69, v69, v153
	v_mul_f32_e32 v70, v70, v153
	v_mul_f32_e32 v71, v71, v153
	v_mul_f32_e32 v72, v72, v153
	v_mul_f32_e32 v73, v73, v153
	v_mul_f32_e32 v74, v74, v153
	v_mul_f32_e32 v75, v75, v153
	v_mul_f32_e32 v64, v64, v153
	v_mul_f32_e32 v65, v65, v153
	v_mul_f32_e32 v66, v66, v153
	v_mul_f32_e32 v67, v67, v153
	v_mul_f32_e32 v170, 0xbfb8aa3b, v76
	v_mul_f32_e32 v171, 0xbfb8aa3b, v77
	v_mul_f32_e32 v172, 0xbfb8aa3b, v78
	v_mul_f32_e32 v173, 0xbfb8aa3b, v79
	v_mul_f32_e32 v174, 0xbfb8aa3b, v68
	v_mul_f32_e32 v175, 0xbfb8aa3b, v69
	v_mul_f32_e32 v176, 0xbfb8aa3b, v70
	v_mul_f32_e32 v177, 0xbfb8aa3b, v71
	v_exp_f32_e32 v170, v170
	v_exp_f32_e32 v171, v171
	v_exp_f32_e32 v172, v172
	v_exp_f32_e32 v173, v173
	v_exp_f32_e32 v174, v174
	v_exp_f32_e32 v175, v175
	v_exp_f32_e32 v176, v176
	v_exp_f32_e32 v177, v177
	v_add_f32_e32 v170, 1.0, v170
	v_add_f32_e32 v171, 1.0, v171
	v_add_f32_e32 v172, 1.0, v172
	v_add_f32_e32 v173, 1.0, v173
	v_add_f32_e32 v174, 1.0, v174
	v_add_f32_e32 v175, 1.0, v175
	v_add_f32_e32 v176, 1.0, v176
	v_add_f32_e32 v177, 1.0, v177
	v_rcp_f32_e32 v170, v170
	v_rcp_f32_e32 v171, v171
	v_rcp_f32_e32 v172, v172
	v_rcp_f32_e32 v173, v173
	v_rcp_f32_e32 v174, v174
	v_rcp_f32_e32 v175, v175
	v_rcp_f32_e32 v176, v176
	v_rcp_f32_e32 v177, v177
	v_mul_f32_e32 v76, v76, v170
	v_mul_f32_e32 v77, v77, v171
	v_mul_f32_e32 v78, v78, v172
	v_mul_f32_e32 v79, v79, v173
	v_mul_f32_e32 v68, v68, v174
	v_mul_f32_e32 v69, v69, v175
	v_mul_f32_e32 v70, v70, v176
	v_mul_f32_e32 v71, v71, v177
	v_mul_f32_e32 v170, v72, v76
	v_mul_f32_e32 v171, v73, v77
	v_mul_f32_e32 v172, v74, v78
	v_mul_f32_e32 v173, v75, v79
	v_mul_f32_e32 v174, v64, v68
	v_mul_f32_e32 v175, v65, v69
	v_mul_f32_e32 v176, v66, v70
	v_mul_f32_e32 v177, v67, v71
	v_cvt_pk_bf16_f32 v64, v170, v171
	v_cvt_pk_bf16_f32 v65, v172, v173
	v_cvt_pk_bf16_f32 v66, v174, v175
	v_cvt_pk_bf16_f32 v67, v176, v177
	v_or_b32_e32 v70, 48, v161
	v_mad_i64_i32 v[68:69], s[6:7], v70, s75, v[112:113]
	v_lshl_add_u64 v[68:69], v[68:69], 0, v[114:115]
	global_store_dwordx4 v[68:69], v[64:67], off
	v_mul_f32_e32 v60, v60, v150
	v_mul_f32_e32 v61, v61, v150
	v_mul_f32_e32 v62, v62, v150
	v_mul_f32_e32 v63, v63, v150
	v_mul_f32_e32 v52, v52, v150
	v_mul_f32_e32 v53, v53, v150
	v_mul_f32_e32 v54, v54, v150
	v_mul_f32_e32 v55, v55, v150
	v_mul_f32_e32 v56, v56, v150
	v_mul_f32_e32 v57, v57, v150
	v_mul_f32_e32 v58, v58, v150
	v_mul_f32_e32 v59, v59, v150
	v_mul_f32_e32 v48, v48, v150
	v_mul_f32_e32 v49, v49, v150
	v_mul_f32_e32 v50, v50, v150
	v_mul_f32_e32 v51, v51, v150
	v_mul_f32_e32 v170, 0xbfb8aa3b, v60
	v_mul_f32_e32 v171, 0xbfb8aa3b, v61
	v_mul_f32_e32 v172, 0xbfb8aa3b, v62
	v_mul_f32_e32 v173, 0xbfb8aa3b, v63
	v_mul_f32_e32 v174, 0xbfb8aa3b, v52
	v_mul_f32_e32 v175, 0xbfb8aa3b, v53
	v_mul_f32_e32 v176, 0xbfb8aa3b, v54
	v_mul_f32_e32 v177, 0xbfb8aa3b, v55
	v_exp_f32_e32 v170, v170
	v_exp_f32_e32 v171, v171
	v_exp_f32_e32 v172, v172
	v_exp_f32_e32 v173, v173
	v_exp_f32_e32 v174, v174
	v_exp_f32_e32 v175, v175
	v_exp_f32_e32 v176, v176
	v_exp_f32_e32 v177, v177
	v_add_f32_e32 v170, 1.0, v170
	v_add_f32_e32 v171, 1.0, v171
	v_add_f32_e32 v172, 1.0, v172
	v_add_f32_e32 v173, 1.0, v173
	v_add_f32_e32 v174, 1.0, v174
	v_add_f32_e32 v175, 1.0, v175
	v_add_f32_e32 v176, 1.0, v176
	v_add_f32_e32 v177, 1.0, v177
	v_rcp_f32_e32 v170, v170
	v_rcp_f32_e32 v171, v171
	v_rcp_f32_e32 v172, v172
	v_rcp_f32_e32 v173, v173
	v_rcp_f32_e32 v174, v174
	v_rcp_f32_e32 v175, v175
	v_rcp_f32_e32 v176, v176
	v_rcp_f32_e32 v177, v177
	v_mul_f32_e32 v60, v60, v170
	v_mul_f32_e32 v61, v61, v171
	v_mul_f32_e32 v62, v62, v172
	v_mul_f32_e32 v63, v63, v173
	v_mul_f32_e32 v52, v52, v174
	v_mul_f32_e32 v53, v53, v175
	v_mul_f32_e32 v54, v54, v176
	v_mul_f32_e32 v55, v55, v177
; __device__ __forceinline__ unsigned cvt_pk_bf16(float lo, float hi) { unsigned r; asm volatile("v_cvt_pk_bf16_f32 %0, %1, %2" : "=v"(r) : "v"(lo), "v"(hi)); return r; }
; __device__ __forceinline__ float fast_sigmoid(float v) { return __builtin_amdgcn_rcpf(1.0f + __expf(-v)); }
;     __device__ __forceinline__ void operator()(const f32x4 (&acc)[2][2][4][2], const Unit& u, int wr, int wc, int fr, int fq) const {
;     ...
;         for (int ai = 0; ai < 2; ++ai)
; #pragma unroll
;             for (int m = 0; m < 4; ++m) {
;                 const int row = row0 + ai * 128 + m * 16; const float s = sc[ai][m];
;                 float a[8];
; #pragma unroll
;                 for (int n = 0; n < 2; ++n) { const f32x4 g = acc[ai][0][m][n] * s, up = acc[ai][1][m][n] * s;
; #pragma unroll
;                     for (int j = 0; j < 4; ++j) a[4 * n + j] = g[j] * fast_sigmoid(g[j]) * up[j]; }
;                 u32x4 w; w.x = cvt_pk_bf16(a[0], a[1]); w.y = cvt_pk_bf16(a[2], a[3]); w.z = cvt_pk_bf16(a[4], a[5]); w.w = cvt_pk_bf16(a[6], a[7]);
;                 *(u32x4*)(act + (size_t)row * FF + col0) = w;
;             }
	v_mul_f32_e32 v170, v56, v60
	v_mul_f32_e32 v171, v57, v61
	v_mul_f32_e32 v172, v58, v62
	v_mul_f32_e32 v173, v59, v63
	v_mul_f32_e32 v174, v48, v52
	v_mul_f32_e32 v175, v49, v53
	v_mul_f32_e32 v176, v50, v54
	v_mul_f32_e32 v177, v51, v55
	v_cvt_pk_bf16_f32 v48, v170, v171
	v_cvt_pk_bf16_f32 v49, v172, v173
	v_cvt_pk_bf16_f32 v50, v174, v175
	v_cvt_pk_bf16_f32 v51, v176, v177
	v_add_u32_e32 v66, 0x80, v161
	v_mad_i64_i32 v[52:53], s[6:7], v66, s75, v[112:113]
	v_lshl_add_u64 v[52:53], v[52:53], 0, v[114:115]
	global_store_dwordx4 v[52:53], v[48:51], off
	v_mul_f32_e32 v44, v44, v151
	v_mul_f32_e32 v45, v45, v151
	v_mul_f32_e32 v46, v46, v151
	v_mul_f32_e32 v47, v47, v151
	v_mul_f32_e32 v36, v36, v151
	v_mul_f32_e32 v37, v37, v151
	v_mul_f32_e32 v38, v38, v151
	v_mul_f32_e32 v39, v39, v151
	v_mul_f32_e32 v40, v40, v151
	v_mul_f32_e32 v41, v41, v151
	v_mul_f32_e32 v42, v42, v151
	v_mul_f32_e32 v43, v43, v151
	v_mul_f32_e32 v32, v32, v151
	v_mul_f32_e32 v33, v33, v151
	v_mul_f32_e32 v34, v34, v151
	v_mul_f32_e32 v35, v35, v151
	v_mul_f32_e32 v170, 0xbfb8aa3b, v44
	v_mul_f32_e32 v171, 0xbfb8aa3b, v45
	v_mul_f32_e32 v172, 0xbfb8aa3b, v46
	v_mul_f32_e32 v173, 0xbfb8aa3b, v47
	v_mul_f32_e32 v174, 0xbfb8aa3b, v36
	v_mul_f32_e32 v175, 0xbfb8aa3b, v37
	v_mul_f32_e32 v176, 0xbfb8aa3b, v38
	v_mul_f32_e32 v177, 0xbfb8aa3b, v39
	v_exp_f32_e32 v170, v170
	v_exp_f32_e32 v171, v171
	v_exp_f32_e32 v172, v172
	v_exp_f32_e32 v173, v173
	v_exp_f32_e32 v174, v174
	v_exp_f32_e32 v175, v175
	v_exp_f32_e32 v176, v176
	v_exp_f32_e32 v177, v177
	v_add_f32_e32 v170, 1.0, v170
	v_add_f32_e32 v171, 1.0, v171
	v_add_f32_e32 v172, 1.0, v172
	v_add_f32_e32 v173, 1.0, v173
	v_add_f32_e32 v174, 1.0, v174
	v_add_f32_e32 v175, 1.0, v175
	v_add_f32_e32 v176, 1.0, v176
	v_add_f32_e32 v177, 1.0, v177
	v_rcp_f32_e32 v170, v170
	v_rcp_f32_e32 v171, v171
	v_rcp_f32_e32 v172, v172
	v_rcp_f32_e32 v173, v173
	v_rcp_f32_e32 v174, v174
	v_rcp_f32_e32 v175, v175
	v_rcp_f32_e32 v176, v176
	v_rcp_f32_e32 v177, v177
	v_mul_f32_e32 v44, v44, v170
	v_mul_f32_e32 v45, v45, v171
	v_mul_f32_e32 v46, v46, v172
	v_mul_f32_e32 v47, v47, v173
	v_mul_f32_e32 v36, v36, v174
	v_mul_f32_e32 v37, v37, v175
	v_mul_f32_e32 v38, v38, v176
	v_mul_f32_e32 v39, v39, v177
	v_mul_f32_e32 v170, v40, v44
	v_mul_f32_e32 v171, v41, v45
	v_mul_f32_e32 v172, v42, v46
	v_mul_f32_e32 v173, v43, v47
	v_mul_f32_e32 v174, v32, v36
	v_mul_f32_e32 v175, v33, v37
	v_mul_f32_e32 v176, v34, v38
	v_mul_f32_e32 v177, v35, v39
	v_cvt_pk_bf16_f32 v32, v170, v171
	v_cvt_pk_bf16_f32 v33, v172, v173
	v_cvt_pk_bf16_f32 v34, v174, v175
	v_cvt_pk_bf16_f32 v35, v176, v177
	v_add_u32_e32 v38, 0x90, v161
	v_mad_i64_i32 v[36:37], s[6:7], v38, s75, v[112:113]
	v_lshl_add_u64 v[36:37], v[36:37], 0, v[114:115]
	global_store_dwordx4 v[36:37], v[32:35], off
	v_mul_f32_e32 v28, v28, v148
	v_mul_f32_e32 v29, v29, v148
	v_mul_f32_e32 v30, v30, v148
	v_mul_f32_e32 v31, v31, v148
	v_mul_f32_e32 v20, v20, v148
	v_mul_f32_e32 v21, v21, v148
	v_mul_f32_e32 v22, v22, v148
	v_mul_f32_e32 v23, v23, v148
	v_mul_f32_e32 v24, v24, v148
	v_mul_f32_e32 v25, v25, v148
	v_mul_f32_e32 v26, v26, v148
	v_mul_f32_e32 v27, v27, v148
	v_mul_f32_e32 v16, v16, v148
	v_mul_f32_e32 v17, v17, v148
	v_mul_f32_e32 v18, v18, v148
	v_mul_f32_e32 v19, v19, v148
	v_mul_f32_e32 v170, 0xbfb8aa3b, v28
	v_mul_f32_e32 v171, 0xbfb8aa3b, v29
	v_mul_f32_e32 v172, 0xbfb8aa3b, v30
	v_mul_f32_e32 v173, 0xbfb8aa3b, v31
	v_mul_f32_e32 v174, 0xbfb8aa3b, v20
	v_mul_f32_e32 v175, 0xbfb8aa3b, v21
	v_mul_f32_e32 v176, 0xbfb8aa3b, v22
	v_mul_f32_e32 v177, 0xbfb8aa3b, v23
	v_exp_f32_e32 v170, v170
	v_exp_f32_e32 v171, v171
	v_exp_f32_e32 v172, v172
	v_exp_f32_e32 v173, v173
; __device__ __forceinline__ unsigned cvt_pk_bf16(float lo, float hi) { unsigned r; asm volatile("v_cvt_pk_bf16_f32 %0, %1, %2" : "=v"(r) : "v"(lo), "v"(hi)); return r; }
; #define PG8_BAR __builtin_amdgcn_s_barrier()
; __device__ __forceinline__ float fast_sigmoid(float v) { return __builtin_amdgcn_rcpf(1.0f + __expf(-v)); }
; template <class Epi, class Sched, bool ALIGN_EPI = false, bool SP2 = false>
; __device__ __forceinline__ void gemm_phase(PG8_LAS unsigned char* lds, const Gemm g, const Sched& S, const Epi& E) {
;     ...
;         if constexpr (!Epi::AFTER_DRAIN) { E(acc, cur, wr, wc, fr, fq); S.done(cur); }
;         if (!has_next) break;
; #pragma unroll
;         for (int a = 0; a < 2; ++a)
; #pragma unroll
;             for (int b = 0; b < 2; ++b)
; #pragma unroll
;                 for (int m = 0; m < 4; ++m)
; #pragma unroll
;                     for (int n = 0; n < 2; ++n) acc[a][b][m][n] = (f32x4){0.f, 0.f, 0.f, 0.f};
;         cur = nxt; cA = nA; cB = nB; ++ui;
;         if constexpr (ALIGN_EPI) { if (wr == 1) PG8_BAR; }
;     __device__ __forceinline__ void operator()(const f32x4 (&acc)[2][2][4][2], const Unit& u, int wr, int wc, int fr, int fq) const {
;     ...
;         for (int ai = 0; ai < 2; ++ai)
; #pragma unroll
;             for (int m = 0; m < 4; ++m) {
;                 const int row = row0 + ai * 128 + m * 16; const float s = sc[ai][m];
;                 float a[8];
; #pragma unroll
;                 for (int n = 0; n < 2; ++n) { const f32x4 g = acc[ai][0][m][n] * s, up = acc[ai][1][m][n] * s;
; #pragma unroll
;                     for (int j = 0; j < 4; ++j) a[4 * n + j] = g[j] * fast_sigmoid(g[j]) * up[j]; }
;                 u32x4 w; w.x = cvt_pk_bf16(a[0], a[1]); w.y = cvt_pk_bf16(a[2], a[3]); w.z = cvt_pk_bf16(a[4], a[5]); w.w = cvt_pk_bf16(a[6], a[7]);
;                 *(u32x4*)(act + (size_t)row * FF + col0) = w;
;             }
	v_exp_f32_e32 v174, v174
	v_exp_f32_e32 v175, v175
	v_exp_f32_e32 v176, v176
	v_exp_f32_e32 v177, v177
	v_add_f32_e32 v170, 1.0, v170
	v_add_f32_e32 v171, 1.0, v171
	v_add_f32_e32 v172, 1.0, v172
	v_add_f32_e32 v173, 1.0, v173
	v_add_f32_e32 v174, 1.0, v174
	v_add_f32_e32 v175, 1.0, v175
	v_add_f32_e32 v176, 1.0, v176
	v_add_f32_e32 v177, 1.0, v177
	v_rcp_f32_e32 v170, v170
	v_rcp_f32_e32 v171, v171
	v_rcp_f32_e32 v172, v172
	v_rcp_f32_e32 v173, v173
	v_rcp_f32_e32 v174, v174
	v_rcp_f32_e32 v175, v175
	v_rcp_f32_e32 v176, v176
	v_rcp_f32_e32 v177, v177
	v_mul_f32_e32 v28, v28, v170
	v_mul_f32_e32 v29, v29, v171
	v_mul_f32_e32 v30, v30, v172
	v_mul_f32_e32 v31, v31, v173
	v_mul_f32_e32 v20, v20, v174
	v_mul_f32_e32 v21, v21, v175
	v_mul_f32_e32 v22, v22, v176
	v_mul_f32_e32 v23, v23, v177
	v_mul_f32_e32 v170, v24, v28
	v_mul_f32_e32 v171, v25, v29
	v_mul_f32_e32 v172, v26, v30
	v_mul_f32_e32 v173, v27, v31
	v_mul_f32_e32 v174, v16, v20
	v_mul_f32_e32 v175, v17, v21
	v_mul_f32_e32 v176, v18, v22
	v_mul_f32_e32 v177, v19, v23
	v_cvt_pk_bf16_f32 v16, v170, v171
	v_cvt_pk_bf16_f32 v17, v172, v173
	v_cvt_pk_bf16_f32 v18, v174, v175
	v_cvt_pk_bf16_f32 v19, v176, v177
	v_add_u32_e32 v22, 0xa0, v161
	v_mad_i64_i32 v[20:21], s[6:7], v22, s75, v[112:113]
	v_lshl_add_u64 v[20:21], v[20:21], 0, v[114:115]
	global_store_dwordx4 v[20:21], v[16:19], off
	v_mul_f32_e32 v12, v12, v149
	v_mul_f32_e32 v13, v13, v149
	v_mul_f32_e32 v14, v14, v149
	v_mul_f32_e32 v15, v15, v149
	v_mul_f32_e32 v4, v4, v149
	v_mul_f32_e32 v5, v5, v149
	v_mul_f32_e32 v6, v6, v149
	v_mul_f32_e32 v7, v7, v149
	v_mul_f32_e32 v8, v8, v149
	v_mul_f32_e32 v9, v9, v149
	v_mul_f32_e32 v10, v10, v149
	v_mul_f32_e32 v11, v11, v149
	v_mul_f32_e32 v0, v0, v149
	v_mul_f32_e32 v1, v1, v149
	v_mul_f32_e32 v2, v2, v149
	v_mul_f32_e32 v3, v3, v149
	v_mul_f32_e32 v170, 0xbfb8aa3b, v12
	v_mul_f32_e32 v171, 0xbfb8aa3b, v13
	v_mul_f32_e32 v172, 0xbfb8aa3b, v14
	v_mul_f32_e32 v173, 0xbfb8aa3b, v15
	v_mul_f32_e32 v174, 0xbfb8aa3b, v4
	v_mul_f32_e32 v175, 0xbfb8aa3b, v5
	v_mul_f32_e32 v176, 0xbfb8aa3b, v6
	v_mul_f32_e32 v177, 0xbfb8aa3b, v7
	v_exp_f32_e32 v170, v170
	v_exp_f32_e32 v171, v171
	v_exp_f32_e32 v172, v172
	v_exp_f32_e32 v173, v173
	v_exp_f32_e32 v174, v174
	v_exp_f32_e32 v175, v175
	v_exp_f32_e32 v176, v176
	v_exp_f32_e32 v177, v177
	v_add_f32_e32 v170, 1.0, v170
	v_add_f32_e32 v171, 1.0, v171
	v_add_f32_e32 v172, 1.0, v172
	v_add_f32_e32 v173, 1.0, v173
	v_add_f32_e32 v174, 1.0, v174
	v_add_f32_e32 v175, 1.0, v175
	v_add_f32_e32 v176, 1.0, v176
	v_add_f32_e32 v177, 1.0, v177
	v_rcp_f32_e32 v170, v170
	v_rcp_f32_e32 v171, v171
	v_rcp_f32_e32 v172, v172
	v_rcp_f32_e32 v173, v173
	v_rcp_f32_e32 v174, v174
	v_rcp_f32_e32 v175, v175
	v_rcp_f32_e32 v176, v176
	v_rcp_f32_e32 v177, v177
	v_mul_f32_e32 v12, v12, v170
	v_mul_f32_e32 v13, v13, v171
	v_mul_f32_e32 v14, v14, v172
	v_mul_f32_e32 v15, v15, v173
	v_mul_f32_e32 v4, v4, v174
	v_mul_f32_e32 v5, v5, v175
	v_mul_f32_e32 v6, v6, v176
	v_mul_f32_e32 v7, v7, v177
	v_mul_f32_e32 v170, v8, v12
	v_mul_f32_e32 v171, v9, v13
	v_mul_f32_e32 v172, v10, v14
	v_mul_f32_e32 v173, v11, v15
	v_mul_f32_e32 v174, v0, v4
	v_mul_f32_e32 v175, v1, v5
	v_mul_f32_e32 v176, v2, v6
	v_mul_f32_e32 v177, v3, v7
	v_cvt_pk_bf16_f32 v0, v170, v171
	v_cvt_pk_bf16_f32 v1, v172, v173
	v_cvt_pk_bf16_f32 v2, v174, v175
	v_cvt_pk_bf16_f32 v3, v176, v177
	v_add_u32_e32 v6, 0xb0, v161
	v_mad_i64_i32 v[4:5], s[6:7], v6, s75, v[112:113]
	v_lshl_add_u64 v[4:5], v[4:5], 0, v[114:115]
	global_store_dwordx4 v[4:5], v[0:3], off
	s_cbranch_vccnz .LBB0_210
	s_andn2_b64 vcc, exec, s[28:29]
	s_cbranch_vccnz .LBB0_209
	s_barrier
	s_branch .LBB0_209

; __device__ __forceinline__ unsigned cvt_pk_bf16(float lo, float hi) { unsigned r; asm volatile("v_cvt_pk_bf16_f32 %0, %1, %2" : "=v"(r) : "v"(lo), "v"(hi)); return r; }
; #define LAS __attribute__((address_space(3)))
; __device__ __forceinline__ float fast_sigmoid(float v) { return __builtin_amdgcn_rcpf(1.0f + __expf(-v)); }
;     __device__ __forceinline__ void operator()(const f32x4 (&acc)[2][2][4][2], const Unit& u, int wr, int wc, int fr, int fq) const {
;         const int row0 = u.pm * 256 + wr * 64 + fr, col0 = u.pn * 128 + wc * 32 + 8 * fq;
;         float sc[2][4];
;         { const LAS float* t_ = rs + ui * 256 + wr * 64 + fr;
; #pragma unroll
;           for (int ai = 0; ai < 2; ++ai)
; #pragma unroll
;               for (int m = 0; m < 4; ++m) sc[ai][m] = t_[ai * 128 + m * 16];
;           ++ui; }
; #pragma unroll
;         for (int ai = 0; ai < 2; ++ai)
; #pragma unroll
;             for (int m = 0; m < 4; ++m) {
;                 const int row = row0 + ai * 128 + m * 16; const float s = sc[ai][m];
;                 float a[8];
; #pragma unroll
;                 for (int n = 0; n < 2; ++n) { const f32x4 g = acc[ai][0][m][n] * s, up = acc[ai][1][m][n] * s;
; #pragma unroll
;                     for (int j = 0; j < 4; ++j) a[4 * n + j] = g[j] * fast_sigmoid(g[j]) * up[j]; }
;                 u32x4 w; w.x = cvt_pk_bf16(a[0], a[1]); w.y = cvt_pk_bf16(a[2], a[3]); w.z = cvt_pk_bf16(a[4], a[5]); w.w = cvt_pk_bf16(a[6], a[7]);
;                 *(u32x4*)(act + (size_t)row * FF + col0) = w;
;             }
.LBB0_904:
	v_lshl_add_u32 v144, s55, 10, v157
	ds_read2_b32 v[168:169], v144 offset1:16
	ds_read2_b32 v[148:149], v144 offset0:32 offset1:48
	ds_read2_b32 v[146:147], v144 offset0:128 offset1:144
	ds_read2_b32 v[144:145], v144 offset0:160 offset1:176
	s_waitcnt lgkmcnt(0)
	v_mul_f32_e32 v124, v124, v168
	v_mul_f32_e32 v125, v125, v168
	v_mul_f32_e32 v126, v126, v168
	v_mul_f32_e32 v127, v127, v168
	v_mul_f32_e32 v116, v116, v168
	v_mul_f32_e32 v117, v117, v168
	v_mul_f32_e32 v118, v118, v168
	v_mul_f32_e32 v119, v119, v168
	v_mul_f32_e32 v120, v120, v168
	v_mul_f32_e32 v121, v121, v168
	v_mul_f32_e32 v122, v122, v168
	v_mul_f32_e32 v123, v123, v168
	v_mul_f32_e32 v112, v112, v168
	v_mul_f32_e32 v113, v113, v168
	v_mul_f32_e32 v114, v114, v168
	v_mul_f32_e32 v115, v115, v168
	v_mul_f32_e32 v174, 0xbfb8aa3b, v124
	v_mul_f32_e32 v175, 0xbfb8aa3b, v125
	v_mul_f32_e32 v176, 0xbfb8aa3b, v126
	v_mul_f32_e32 v177, 0xbfb8aa3b, v127
	v_mul_f32_e32 v178, 0xbfb8aa3b, v116
	v_mul_f32_e32 v179, 0xbfb8aa3b, v117
	v_mul_f32_e32 v180, 0xbfb8aa3b, v118
	v_mul_f32_e32 v181, 0xbfb8aa3b, v119
	v_exp_f32_e32 v174, v174
	v_exp_f32_e32 v175, v175
	v_exp_f32_e32 v176, v176
	v_exp_f32_e32 v177, v177
	v_exp_f32_e32 v178, v178
	v_exp_f32_e32 v179, v179
	v_exp_f32_e32 v180, v180
	v_exp_f32_e32 v181, v181
	v_add_f32_e32 v174, 1.0, v174
	v_add_f32_e32 v175, 1.0, v175
	v_add_f32_e32 v176, 1.0, v176
	v_add_f32_e32 v177, 1.0, v177
	v_add_f32_e32 v178, 1.0, v178
	v_add_f32_e32 v179, 1.0, v179
	v_add_f32_e32 v180, 1.0, v180
	v_add_f32_e32 v181, 1.0, v181
	v_rcp_f32_e32 v174, v174
	v_rcp_f32_e32 v175, v175
	v_rcp_f32_e32 v176, v176
	v_rcp_f32_e32 v177, v177
	v_rcp_f32_e32 v178, v178
	v_rcp_f32_e32 v179, v179
	v_rcp_f32_e32 v180, v180
	v_rcp_f32_e32 v181, v181
	v_mul_f32_e32 v124, v124, v174
	v_mul_f32_e32 v125, v125, v175
	v_mul_f32_e32 v126, v126, v176
	v_mul_f32_e32 v127, v127, v177
	v_mul_f32_e32 v116, v116, v178
	v_mul_f32_e32 v117, v117, v179
	v_mul_f32_e32 v118, v118, v180
	v_mul_f32_e32 v119, v119, v181
	v_mul_f32_e32 v174, v120, v124
	v_mul_f32_e32 v175, v121, v125
	v_mul_f32_e32 v176, v122, v126
	v_mul_f32_e32 v177, v123, v127
	v_mul_f32_e32 v178, v112, v116
	v_mul_f32_e32 v179, v113, v117
	v_mul_f32_e32 v180, v114, v118
	v_mul_f32_e32 v181, v115, v119
	v_cvt_pk_bf16_f32 v116, v174, v175
	v_cvt_pk_bf16_f32 v117, v176, v177
	v_cvt_pk_bf16_f32 v118, v178, v179
	v_cvt_pk_bf16_f32 v119, v180, v181
	v_lshl_or_b32 v170, s75, 7, v158
	v_lshl_add_u32 v167, s54, 8, v155
	v_ashrrev_i32_e32 v171, 31, v170
	s_mov_b64 s[54:55], -1
	s_andn2_b64 vcc, exec, s[46:47]
	v_mov_b64_e32 v[112:113], s[24:25]
	v_mad_i64_i32 v[120:121], s[6:7], v167, s69, v[112:113]
	v_lshlrev_b64 v[114:115], 1, v[170:171]
	v_lshl_add_u64 v[120:121], v[120:121], 0, v[114:115]
	global_store_dwordx4 v[120:121], v[116:119], off
	v_mul_f32_e32 v108, v108, v169
	v_mul_f32_e32 v109, v109, v169
	v_mul_f32_e32 v110, v110, v169
	v_mul_f32_e32 v111, v111, v169
	v_mul_f32_e32 v100, v100, v169
	v_mul_f32_e32 v101, v101, v169
	v_mul_f32_e32 v102, v102, v169
	v_mul_f32_e32 v103, v103, v169
	v_mul_f32_e32 v104, v104, v169
	v_mul_f32_e32 v105, v105, v169
	v_mul_f32_e32 v106, v106, v169
	v_mul_f32_e32 v107, v107, v169
	v_mul_f32_e32 v96, v96, v169
	v_mul_f32_e32 v97, v97, v169
	v_mul_f32_e32 v98, v98, v169
	v_mul_f32_e32 v99, v99, v169
	v_mul_f32_e32 v174, 0xbfb8aa3b, v108
	v_mul_f32_e32 v175, 0xbfb8aa3b, v109
	v_mul_f32_e32 v176, 0xbfb8aa3b, v110
	v_mul_f32_e32 v177, 0xbfb8aa3b, v111
	v_mul_f32_e32 v178, 0xbfb8aa3b, v100
	v_mul_f32_e32 v179, 0xbfb8aa3b, v101
	v_mul_f32_e32 v180, 0xbfb8aa3b, v102
	v_mul_f32_e32 v181, 0xbfb8aa3b, v103
	v_exp_f32_e32 v174, v174
	v_exp_f32_e32 v175, v175
	v_exp_f32_e32 v176, v176
	v_exp_f32_e32 v177, v177
	v_exp_f32_e32 v178, v178
	v_exp_f32_e32 v179, v179
	v_exp_f32_e32 v180, v180
	v_exp_f32_e32 v181, v181
	v_add_f32_e32 v174, 1.0, v174
	v_add_f32_e32 v175, 1.0, v175
	v_add_f32_e32 v176, 1.0, v176
	v_add_f32_e32 v177, 1.0, v177
	v_add_f32_e32 v178, 1.0, v178
	v_add_f32_e32 v179, 1.0, v179
	v_add_f32_e32 v180, 1.0, v180
	v_add_f32_e32 v181, 1.0, v181
	v_rcp_f32_e32 v174, v174
	v_rcp_f32_e32 v175, v175
	v_rcp_f32_e32 v176, v176
	v_rcp_f32_e32 v177, v177
	v_rcp_f32_e32 v178, v178
	v_rcp_f32_e32 v179, v179
	v_rcp_f32_e32 v180, v180
	v_rcp_f32_e32 v181, v181
	v_mul_f32_e32 v108, v108, v174
	v_mul_f32_e32 v109, v109, v175
	v_mul_f32_e32 v110, v110, v176
	v_mul_f32_e32 v111, v111, v177
	v_mul_f32_e32 v100, v100, v178
	v_mul_f32_e32 v101, v101, v179
	v_mul_f32_e32 v102, v102, v180
	v_mul_f32_e32 v103, v103, v181
	v_mul_f32_e32 v174, v104, v108
	v_mul_f32_e32 v175, v105, v109
	v_mul_f32_e32 v176, v106, v110
	v_mul_f32_e32 v177, v107, v111
	v_mul_f32_e32 v178, v96, v100
	v_mul_f32_e32 v179, v97, v101
	v_mul_f32_e32 v180, v98, v102
	v_mul_f32_e32 v181, v99, v103
	v_cvt_pk_bf16_f32 v96, v174, v175
	v_cvt_pk_bf16_f32 v97, v176, v177
	v_cvt_pk_bf16_f32 v98, v178, v179
	v_cvt_pk_bf16_f32 v99, v180, v181
	v_or_b32_e32 v102, 16, v167
	v_mad_i64_i32 v[100:101], s[6:7], v102, s69, v[112:113]
	v_lshl_add_u64 v[100:101], v[100:101], 0, v[114:115]
	global_store_dwordx4 v[100:101], v[96:99], off
	v_mul_f32_e32 v92, v92, v148
	v_mul_f32_e32 v93, v93, v148
	v_mul_f32_e32 v94, v94, v148
	v_mul_f32_e32 v95, v95, v148
	v_mul_f32_e32 v84, v84, v148
	v_mul_f32_e32 v85, v85, v148
	v_mul_f32_e32 v86, v86, v148
	v_mul_f32_e32 v87, v87, v148
	v_mul_f32_e32 v88, v88, v148
	v_mul_f32_e32 v89, v89, v148
	v_mul_f32_e32 v90, v90, v148
	v_mul_f32_e32 v91, v91, v148
	v_mul_f32_e32 v80, v80, v148
	v_mul_f32_e32 v81, v81, v148
	v_mul_f32_e32 v82, v82, v148
	v_mul_f32_e32 v83, v83, v148
	v_mul_f32_e32 v174, 0xbfb8aa3b, v92
; __device__ __forceinline__ unsigned cvt_pk_bf16(float lo, float hi) { unsigned r; asm volatile("v_cvt_pk_bf16_f32 %0, %1, %2" : "=v"(r) : "v"(lo), "v"(hi)); return r; }
; __device__ __forceinline__ float fast_sigmoid(float v) { return __builtin_amdgcn_rcpf(1.0f + __expf(-v)); }
;     __device__ __forceinline__ void operator()(const f32x4 (&acc)[2][2][4][2], const Unit& u, int wr, int wc, int fr, int fq) const {
;     ...
;         for (int ai = 0; ai < 2; ++ai)
; #pragma unroll
;             for (int m = 0; m < 4; ++m) {
;                 const int row = row0 + ai * 128 + m * 16; const float s = sc[ai][m];
;                 float a[8];
; #pragma unroll
;                 for (int n = 0; n < 2; ++n) { const f32x4 g = acc[ai][0][m][n] * s, up = acc[ai][1][m][n] * s;
; #pragma unroll
;                     for (int j = 0; j < 4; ++j) a[4 * n + j] = g[j] * fast_sigmoid(g[j]) * up[j]; }
;                 u32x4 w; w.x = cvt_pk_bf16(a[0], a[1]); w.y = cvt_pk_bf16(a[2], a[3]); w.z = cvt_pk_bf16(a[4], a[5]); w.w = cvt_pk_bf16(a[6], a[7]);
;                 *(u32x4*)(act + (size_t)row * FF + col0) = w;
;             }
	v_mul_f32_e32 v175, 0xbfb8aa3b, v93
	v_mul_f32_e32 v176, 0xbfb8aa3b, v94
	v_mul_f32_e32 v177, 0xbfb8aa3b, v95
	v_mul_f32_e32 v178, 0xbfb8aa3b, v84
	v_mul_f32_e32 v179, 0xbfb8aa3b, v85
	v_mul_f32_e32 v180, 0xbfb8aa3b, v86
	v_mul_f32_e32 v181, 0xbfb8aa3b, v87
	v_exp_f32_e32 v174, v174
	v_exp_f32_e32 v175, v175
	v_exp_f32_e32 v176, v176
	v_exp_f32_e32 v177, v177
	v_exp_f32_e32 v178, v178
	v_exp_f32_e32 v179, v179
	v_exp_f32_e32 v180, v180
	v_exp_f32_e32 v181, v181
	v_add_f32_e32 v174, 1.0, v174
	v_add_f32_e32 v175, 1.0, v175
	v_add_f32_e32 v176, 1.0, v176
	v_add_f32_e32 v177, 1.0, v177
	v_add_f32_e32 v178, 1.0, v178
	v_add_f32_e32 v179, 1.0, v179
	v_add_f32_e32 v180, 1.0, v180
	v_add_f32_e32 v181, 1.0, v181
	v_rcp_f32_e32 v174, v174
	v_rcp_f32_e32 v175, v175
	v_rcp_f32_e32 v176, v176
	v_rcp_f32_e32 v177, v177
	v_rcp_f32_e32 v178, v178
	v_rcp_f32_e32 v179, v179
	v_rcp_f32_e32 v180, v180
	v_rcp_f32_e32 v181, v181
	v_mul_f32_e32 v92, v92, v174
	v_mul_f32_e32 v93, v93, v175
	v_mul_f32_e32 v94, v94, v176
	v_mul_f32_e32 v95, v95, v177
	v_mul_f32_e32 v84, v84, v178
	v_mul_f32_e32 v85, v85, v179
	v_mul_f32_e32 v86, v86, v180
	v_mul_f32_e32 v87, v87, v181
	v_mul_f32_e32 v174, v88, v92
	v_mul_f32_e32 v175, v89, v93
	v_mul_f32_e32 v176, v90, v94
	v_mul_f32_e32 v177, v91, v95
	v_mul_f32_e32 v178, v80, v84
	v_mul_f32_e32 v179, v81, v85
	v_mul_f32_e32 v180, v82, v86
	v_mul_f32_e32 v181, v83, v87
	v_cvt_pk_bf16_f32 v80, v174, v175
	v_cvt_pk_bf16_f32 v81, v176, v177
	v_cvt_pk_bf16_f32 v82, v178, v179
	v_cvt_pk_bf16_f32 v83, v180, v181
	v_or_b32_e32 v86, 32, v167
	v_mad_i64_i32 v[84:85], s[6:7], v86, s69, v[112:113]
	v_lshl_add_u64 v[84:85], v[84:85], 0, v[114:115]
	global_store_dwordx4 v[84:85], v[80:83], off
	v_mul_f32_e32 v76, v76, v149
	v_mul_f32_e32 v77, v77, v149
	v_mul_f32_e32 v78, v78, v149
	v_mul_f32_e32 v79, v79, v149
	v_mul_f32_e32 v68, v68, v149
	v_mul_f32_e32 v69, v69, v149
	v_mul_f32_e32 v70, v70, v149
	v_mul_f32_e32 v71, v71, v149
	v_mul_f32_e32 v72, v72, v149
	v_mul_f32_e32 v73, v73, v149
	v_mul_f32_e32 v74, v74, v149
	v_mul_f32_e32 v75, v75, v149
	v_mul_f32_e32 v64, v64, v149
	v_mul_f32_e32 v65, v65, v149
	v_mul_f32_e32 v66, v66, v149
	v_mul_f32_e32 v67, v67, v149
	v_mul_f32_e32 v174, 0xbfb8aa3b, v76
	v_mul_f32_e32 v175, 0xbfb8aa3b, v77
	v_mul_f32_e32 v176, 0xbfb8aa3b, v78
	v_mul_f32_e32 v177, 0xbfb8aa3b, v79
	v_mul_f32_e32 v178, 0xbfb8aa3b, v68
	v_mul_f32_e32 v179, 0xbfb8aa3b, v69
	v_mul_f32_e32 v180, 0xbfb8aa3b, v70
	v_mul_f32_e32 v181, 0xbfb8aa3b, v71
	v_exp_f32_e32 v174, v174
	v_exp_f32_e32 v175, v175
	v_exp_f32_e32 v176, v176
	v_exp_f32_e32 v177, v177
	v_exp_f32_e32 v178, v178
	v_exp_f32_e32 v179, v179
	v_exp_f32_e32 v180, v180
	v_exp_f32_e32 v181, v181
	v_add_f32_e32 v174, 1.0, v174
	v_add_f32_e32 v175, 1.0, v175
	v_add_f32_e32 v176, 1.0, v176
	v_add_f32_e32 v177, 1.0, v177
	v_add_f32_e32 v178, 1.0, v178
	v_add_f32_e32 v179, 1.0, v179
	v_add_f32_e32 v180, 1.0, v180
	v_add_f32_e32 v181, 1.0, v181
	v_rcp_f32_e32 v174, v174
	v_rcp_f32_e32 v175, v175
	v_rcp_f32_e32 v176, v176
	v_rcp_f32_e32 v177, v177
	v_rcp_f32_e32 v178, v178
	v_rcp_f32_e32 v179, v179
	v_rcp_f32_e32 v180, v180
	v_rcp_f32_e32 v181, v181
	v_mul_f32_e32 v76, v76, v174
	v_mul_f32_e32 v77, v77, v175
	v_mul_f32_e32 v78, v78, v176
	v_mul_f32_e32 v79, v79, v177
	v_mul_f32_e32 v68, v68, v178
	v_mul_f32_e32 v69, v69, v179
	v_mul_f32_e32 v70, v70, v180
	v_mul_f32_e32 v71, v71, v181
	v_mul_f32_e32 v174, v72, v76
	v_mul_f32_e32 v175, v73, v77
	v_mul_f32_e32 v176, v74, v78
	v_mul_f32_e32 v177, v75, v79
	v_mul_f32_e32 v178, v64, v68
	v_mul_f32_e32 v179, v65, v69
	v_mul_f32_e32 v180, v66, v70
	v_mul_f32_e32 v181, v67, v71
	v_cvt_pk_bf16_f32 v64, v174, v175
	v_cvt_pk_bf16_f32 v65, v176, v177
	v_cvt_pk_bf16_f32 v66, v178, v179
	v_cvt_pk_bf16_f32 v67, v180, v181
	v_or_b32_e32 v70, 48, v167
	v_mad_i64_i32 v[68:69], s[6:7], v70, s69, v[112:113]
	v_lshl_add_u64 v[68:69], v[68:69], 0, v[114:115]
	global_store_dwordx4 v[68:69], v[64:67], off
	v_mul_f32_e32 v60, v60, v146
	v_mul_f32_e32 v61, v61, v146
	v_mul_f32_e32 v62, v62, v146
	v_mul_f32_e32 v63, v63, v146
	v_mul_f32_e32 v52, v52, v146
	v_mul_f32_e32 v53, v53, v146
	v_mul_f32_e32 v54, v54, v146
	v_mul_f32_e32 v55, v55, v146
	v_mul_f32_e32 v56, v56, v146
	v_mul_f32_e32 v57, v57, v146
	v_mul_f32_e32 v58, v58, v146
	v_mul_f32_e32 v59, v59, v146
	v_mul_f32_e32 v48, v48, v146
	v_mul_f32_e32 v49, v49, v146
	v_mul_f32_e32 v50, v50, v146
	v_mul_f32_e32 v51, v51, v146
	v_mul_f32_e32 v174, 0xbfb8aa3b, v60
	v_mul_f32_e32 v175, 0xbfb8aa3b, v61
	v_mul_f32_e32 v176, 0xbfb8aa3b, v62
	v_mul_f32_e32 v177, 0xbfb8aa3b, v63
	v_mul_f32_e32 v178, 0xbfb8aa3b, v52
	v_mul_f32_e32 v179, 0xbfb8aa3b, v53
	v_mul_f32_e32 v180, 0xbfb8aa3b, v54
	v_mul_f32_e32 v181, 0xbfb8aa3b, v55
	v_exp_f32_e32 v174, v174
	v_exp_f32_e32 v175, v175
	v_exp_f32_e32 v176, v176
	v_exp_f32_e32 v177, v177
	v_exp_f32_e32 v178, v178
	v_exp_f32_e32 v179, v179
	v_exp_f32_e32 v180, v180
	v_exp_f32_e32 v181, v181
	v_add_f32_e32 v174, 1.0, v174
	v_add_f32_e32 v175, 1.0, v175
	v_add_f32_e32 v176, 1.0, v176
	v_add_f32_e32 v177, 1.0, v177
	v_add_f32_e32 v178, 1.0, v178
	v_add_f32_e32 v179, 1.0, v179
	v_add_f32_e32 v180, 1.0, v180
	v_add_f32_e32 v181, 1.0, v181
	v_rcp_f32_e32 v174, v174
	v_rcp_f32_e32 v175, v175
	v_rcp_f32_e32 v176, v176
	v_rcp_f32_e32 v177, v177
	v_rcp_f32_e32 v178, v178
	v_rcp_f32_e32 v179, v179
	v_rcp_f32_e32 v180, v180
	v_rcp_f32_e32 v181, v181
	v_mul_f32_e32 v60, v60, v174
	v_mul_f32_e32 v61, v61, v175
	v_mul_f32_e32 v62, v62, v176
	v_mul_f32_e32 v63, v63, v177
	v_mul_f32_e32 v52, v52, v178
	v_mul_f32_e32 v53, v53, v179
	v_mul_f32_e32 v54, v54, v180
	v_mul_f32_e32 v55, v55, v181
; __device__ __forceinline__ unsigned cvt_pk_bf16(float lo, float hi) { unsigned r; asm volatile("v_cvt_pk_bf16_f32 %0, %1, %2" : "=v"(r) : "v"(lo), "v"(hi)); return r; }
; __device__ __forceinline__ float fast_sigmoid(float v) { return __builtin_amdgcn_rcpf(1.0f + __expf(-v)); }
;     __device__ __forceinline__ void operator()(const f32x4 (&acc)[2][2][4][2], const Unit& u, int wr, int wc, int fr, int fq) const {
;     ...
;         for (int ai = 0; ai < 2; ++ai)
; #pragma unroll
;             for (int m = 0; m < 4; ++m) {
;                 const int row = row0 + ai * 128 + m * 16; const float s = sc[ai][m];
;                 float a[8];
; #pragma unroll
;                 for (int n = 0; n < 2; ++n) { const f32x4 g = acc[ai][0][m][n] * s, up = acc[ai][1][m][n] * s;
; #pragma unroll
;                     for (int j = 0; j < 4; ++j) a[4 * n + j] = g[j] * fast_sigmoid(g[j]) * up[j]; }
;                 u32x4 w; w.x = cvt_pk_bf16(a[0], a[1]); w.y = cvt_pk_bf16(a[2], a[3]); w.z = cvt_pk_bf16(a[4], a[5]); w.w = cvt_pk_bf16(a[6], a[7]);
;                 *(u32x4*)(act + (size_t)row * FF + col0) = w;
;             }
	v_mul_f32_e32 v174, v56, v60
	v_mul_f32_e32 v175, v57, v61
	v_mul_f32_e32 v176, v58, v62
	v_mul_f32_e32 v177, v59, v63
	v_mul_f32_e32 v178, v48, v52
	v_mul_f32_e32 v179, v49, v53
	v_mul_f32_e32 v180, v50, v54
	v_mul_f32_e32 v181, v51, v55
	v_cvt_pk_bf16_f32 v48, v174, v175
	v_cvt_pk_bf16_f32 v49, v176, v177
	v_cvt_pk_bf16_f32 v50, v178, v179
	v_cvt_pk_bf16_f32 v51, v180, v181
	v_add_u32_e32 v66, 0x80, v167
	v_mad_i64_i32 v[52:53], s[6:7], v66, s69, v[112:113]
	v_lshl_add_u64 v[52:53], v[52:53], 0, v[114:115]
	global_store_dwordx4 v[52:53], v[48:51], off
	v_mul_f32_e32 v44, v44, v147
	v_mul_f32_e32 v45, v45, v147
	v_mul_f32_e32 v46, v46, v147
	v_mul_f32_e32 v47, v47, v147
	v_mul_f32_e32 v36, v36, v147
	v_mul_f32_e32 v37, v37, v147
	v_mul_f32_e32 v38, v38, v147
	v_mul_f32_e32 v39, v39, v147
	v_mul_f32_e32 v40, v40, v147
	v_mul_f32_e32 v41, v41, v147
	v_mul_f32_e32 v42, v42, v147
	v_mul_f32_e32 v43, v43, v147
	v_mul_f32_e32 v32, v32, v147
	v_mul_f32_e32 v33, v33, v147
	v_mul_f32_e32 v34, v34, v147
	v_mul_f32_e32 v35, v35, v147
	v_mul_f32_e32 v174, 0xbfb8aa3b, v44
	v_mul_f32_e32 v175, 0xbfb8aa3b, v45
	v_mul_f32_e32 v176, 0xbfb8aa3b, v46
	v_mul_f32_e32 v177, 0xbfb8aa3b, v47
	v_mul_f32_e32 v178, 0xbfb8aa3b, v36
	v_mul_f32_e32 v179, 0xbfb8aa3b, v37
	v_mul_f32_e32 v180, 0xbfb8aa3b, v38
	v_mul_f32_e32 v181, 0xbfb8aa3b, v39
	v_exp_f32_e32 v174, v174
	v_exp_f32_e32 v175, v175
	v_exp_f32_e32 v176, v176
	v_exp_f32_e32 v177, v177
	v_exp_f32_e32 v178, v178
	v_exp_f32_e32 v179, v179
	v_exp_f32_e32 v180, v180
	v_exp_f32_e32 v181, v181
	v_add_f32_e32 v174, 1.0, v174
	v_add_f32_e32 v175, 1.0, v175
	v_add_f32_e32 v176, 1.0, v176
	v_add_f32_e32 v177, 1.0, v177
	v_add_f32_e32 v178, 1.0, v178
	v_add_f32_e32 v179, 1.0, v179
	v_add_f32_e32 v180, 1.0, v180
	v_add_f32_e32 v181, 1.0, v181
	v_rcp_f32_e32 v174, v174
	v_rcp_f32_e32 v175, v175
	v_rcp_f32_e32 v176, v176
	v_rcp_f32_e32 v177, v177
	v_rcp_f32_e32 v178, v178
	v_rcp_f32_e32 v179, v179
	v_rcp_f32_e32 v180, v180
	v_rcp_f32_e32 v181, v181
	v_mul_f32_e32 v44, v44, v174
	v_mul_f32_e32 v45, v45, v175
	v_mul_f32_e32 v46, v46, v176
	v_mul_f32_e32 v47, v47, v177
	v_mul_f32_e32 v36, v36, v178
	v_mul_f32_e32 v37, v37, v179
	v_mul_f32_e32 v38, v38, v180
	v_mul_f32_e32 v39, v39, v181
	v_mul_f32_e32 v174, v40, v44
	v_mul_f32_e32 v175, v41, v45
	v_mul_f32_e32 v176, v42, v46
	v_mul_f32_e32 v177, v43, v47
	v_mul_f32_e32 v178, v32, v36
	v_mul_f32_e32 v179, v33, v37
	v_mul_f32_e32 v180, v34, v38
	v_mul_f32_e32 v181, v35, v39
	v_cvt_pk_bf16_f32 v32, v174, v175
	v_cvt_pk_bf16_f32 v33, v176, v177
	v_cvt_pk_bf16_f32 v34, v178, v179
	v_cvt_pk_bf16_f32 v35, v180, v181
	v_add_u32_e32 v38, 0x90, v167
	v_mad_i64_i32 v[36:37], s[6:7], v38, s69, v[112:113]
	v_lshl_add_u64 v[36:37], v[36:37], 0, v[114:115]
	global_store_dwordx4 v[36:37], v[32:35], off
	v_mul_f32_e32 v28, v28, v144
	v_mul_f32_e32 v29, v29, v144
	v_mul_f32_e32 v30, v30, v144
	v_mul_f32_e32 v31, v31, v144
	v_mul_f32_e32 v20, v20, v144
	v_mul_f32_e32 v21, v21, v144
	v_mul_f32_e32 v22, v22, v144
	v_mul_f32_e32 v23, v23, v144
	v_mul_f32_e32 v24, v24, v144
	v_mul_f32_e32 v25, v25, v144
	v_mul_f32_e32 v26, v26, v144
	v_mul_f32_e32 v27, v27, v144
	v_mul_f32_e32 v16, v16, v144
	v_mul_f32_e32 v17, v17, v144
	v_mul_f32_e32 v18, v18, v144
	v_mul_f32_e32 v19, v19, v144
	v_mul_f32_e32 v174, 0xbfb8aa3b, v28
	v_mul_f32_e32 v175, 0xbfb8aa3b, v29
	v_mul_f32_e32 v176, 0xbfb8aa3b, v30
	v_mul_f32_e32 v177, 0xbfb8aa3b, v31
	v_mul_f32_e32 v178, 0xbfb8aa3b, v20
	v_mul_f32_e32 v179, 0xbfb8aa3b, v21
	v_mul_f32_e32 v180, 0xbfb8aa3b, v22
	v_mul_f32_e32 v181, 0xbfb8aa3b, v23
	v_exp_f32_e32 v174, v174
	v_exp_f32_e32 v175, v175
	v_exp_f32_e32 v176, v176
	v_exp_f32_e32 v177, v177
; __device__ __forceinline__ unsigned cvt_pk_bf16(float lo, float hi) { unsigned r; asm volatile("v_cvt_pk_bf16_f32 %0, %1, %2" : "=v"(r) : "v"(lo), "v"(hi)); return r; }
; __device__ __forceinline__ float fast_sigmoid(float v) { return __builtin_amdgcn_rcpf(1.0f + __expf(-v)); }
;     __device__ __forceinline__ void operator()(const f32x4 (&acc)[2][2][4][2], const Unit& u, int wr, int wc, int fr, int fq) const {
;     ...
; #pragma unroll
;         for (int ai = 0; ai < 2; ++ai)
; #pragma unroll
;             for (int m = 0; m < 4; ++m) {
;                 const int row = row0 + ai * 128 + m * 16; const float s = sc[ai][m];
;                 float a[8];
; #pragma unroll
;                 for (int n = 0; n < 2; ++n) { const f32x4 g = acc[ai][0][m][n] * s, up = acc[ai][1][m][n] * s;
; #pragma unroll
;                     for (int j = 0; j < 4; ++j) a[4 * n + j] = g[j] * fast_sigmoid(g[j]) * up[j]; }
;                 u32x4 w; w.x = cvt_pk_bf16(a[0], a[1]); w.y = cvt_pk_bf16(a[2], a[3]); w.z = cvt_pk_bf16(a[4], a[5]); w.w = cvt_pk_bf16(a[6], a[7]);
;                 *(u32x4*)(act + (size_t)row * FF + col0) = w;
;             }
	v_exp_f32_e32 v178, v178
	v_exp_f32_e32 v179, v179
	v_exp_f32_e32 v180, v180
	v_exp_f32_e32 v181, v181
	v_add_f32_e32 v174, 1.0, v174
	v_add_f32_e32 v175, 1.0, v175
	v_add_f32_e32 v176, 1.0, v176
	v_add_f32_e32 v177, 1.0, v177
	v_add_f32_e32 v178, 1.0, v178
	v_add_f32_e32 v179, 1.0, v179
	v_add_f32_e32 v180, 1.0, v180
	v_add_f32_e32 v181, 1.0, v181
	v_rcp_f32_e32 v174, v174
	v_rcp_f32_e32 v175, v175
	v_rcp_f32_e32 v176, v176
	v_rcp_f32_e32 v177, v177
	v_rcp_f32_e32 v178, v178
	v_rcp_f32_e32 v179, v179
	v_rcp_f32_e32 v180, v180
	v_rcp_f32_e32 v181, v181
	v_mul_f32_e32 v28, v28, v174
	v_mul_f32_e32 v29, v29, v175
	v_mul_f32_e32 v30, v30, v176
	v_mul_f32_e32 v31, v31, v177
	v_mul_f32_e32 v20, v20, v178
	v_mul_f32_e32 v21, v21, v179
	v_mul_f32_e32 v22, v22, v180
	v_mul_f32_e32 v23, v23, v181
	v_mul_f32_e32 v174, v24, v28
	v_mul_f32_e32 v175, v25, v29
	v_mul_f32_e32 v176, v26, v30
	v_mul_f32_e32 v177, v27, v31
	v_mul_f32_e32 v178, v16, v20
	v_mul_f32_e32 v179, v17, v21
	v_mul_f32_e32 v180, v18, v22
	v_mul_f32_e32 v181, v19, v23
	v_cvt_pk_bf16_f32 v16, v174, v175
	v_cvt_pk_bf16_f32 v17, v176, v177
	v_cvt_pk_bf16_f32 v18, v178, v179
	v_cvt_pk_bf16_f32 v19, v180, v181
	v_add_u32_e32 v22, 0xa0, v167
	v_mad_i64_i32 v[20:21], s[6:7], v22, s69, v[112:113]
	v_lshl_add_u64 v[20:21], v[20:21], 0, v[114:115]
	global_store_dwordx4 v[20:21], v[16:19], off
	v_mul_f32_e32 v12, v12, v145
	v_mul_f32_e32 v13, v13, v145
	v_mul_f32_e32 v14, v14, v145
	v_mul_f32_e32 v15, v15, v145
	v_mul_f32_e32 v4, v4, v145
	v_mul_f32_e32 v5, v5, v145
	v_mul_f32_e32 v6, v6, v145
	v_mul_f32_e32 v7, v7, v145
	v_mul_f32_e32 v8, v8, v145
	v_mul_f32_e32 v9, v9, v145
	v_mul_f32_e32 v10, v10, v145
	v_mul_f32_e32 v11, v11, v145
	v_mul_f32_e32 v0, v0, v145
	v_mul_f32_e32 v1, v1, v145
	v_mul_f32_e32 v2, v2, v145
	v_mul_f32_e32 v3, v3, v145
	v_mul_f32_e32 v174, 0xbfb8aa3b, v12
	v_mul_f32_e32 v175, 0xbfb8aa3b, v13
	v_mul_f32_e32 v176, 0xbfb8aa3b, v14
	v_mul_f32_e32 v177, 0xbfb8aa3b, v15
	v_mul_f32_e32 v178, 0xbfb8aa3b, v4
	v_mul_f32_e32 v179, 0xbfb8aa3b, v5
	v_mul_f32_e32 v180, 0xbfb8aa3b, v6
	v_mul_f32_e32 v181, 0xbfb8aa3b, v7
	v_exp_f32_e32 v174, v174
	v_exp_f32_e32 v175, v175
	v_exp_f32_e32 v176, v176
	v_exp_f32_e32 v177, v177
	v_exp_f32_e32 v178, v178
	v_exp_f32_e32 v179, v179
	v_exp_f32_e32 v180, v180
	v_exp_f32_e32 v181, v181
	v_add_f32_e32 v174, 1.0, v174
	v_add_f32_e32 v175, 1.0, v175
	v_add_f32_e32 v176, 1.0, v176
	v_add_f32_e32 v177, 1.0, v177
	v_add_f32_e32 v178, 1.0, v178
	v_add_f32_e32 v179, 1.0, v179
	v_add_f32_e32 v180, 1.0, v180
	v_add_f32_e32 v181, 1.0, v181
	v_rcp_f32_e32 v174, v174
	v_rcp_f32_e32 v175, v175
	v_rcp_f32_e32 v176, v176
	v_rcp_f32_e32 v177, v177
	v_rcp_f32_e32 v178, v178
	v_rcp_f32_e32 v179, v179
	v_rcp_f32_e32 v180, v180
	v_rcp_f32_e32 v181, v181
	v_mul_f32_e32 v12, v12, v174
	v_mul_f32_e32 v13, v13, v175
	v_mul_f32_e32 v14, v14, v176
	v_mul_f32_e32 v15, v15, v177
	v_mul_f32_e32 v4, v4, v178
	v_mul_f32_e32 v5, v5, v179
	v_mul_f32_e32 v6, v6, v180
	v_mul_f32_e32 v7, v7, v181
	v_mul_f32_e32 v174, v8, v12
	v_mul_f32_e32 v175, v9, v13
	v_mul_f32_e32 v176, v10, v14
	v_mul_f32_e32 v177, v11, v15
	v_mul_f32_e32 v178, v0, v4
	v_mul_f32_e32 v179, v1, v5
	v_mul_f32_e32 v180, v2, v6
	v_mul_f32_e32 v181, v3, v7
	v_cvt_pk_bf16_f32 v0, v174, v175
	v_cvt_pk_bf16_f32 v1, v176, v177
	v_cvt_pk_bf16_f32 v2, v178, v179
	v_cvt_pk_bf16_f32 v3, v180, v181
	v_add_u32_e32 v6, 0xb0, v167
	v_mad_i64_i32 v[4:5], s[6:7], v6, s69, v[112:113]
	v_lshl_add_u64 v[4:5], v[4:5], 0, v[114:115]
	global_store_dwordx4 v[4:5], v[0:3], off
	s_cbranch_vccnz .LBB0_893
	s_andn2_b64 vcc, exec, s[28:29]
	s_cbranch_vccnz .LBB0_892
	s_barrier
	s_branch .LBB0_892

; __device__ __forceinline__ unsigned cvt_pk_bf16(float lo, float hi) { unsigned r; asm volatile("v_cvt_pk_bf16_f32 %0, %1, %2" : "=v"(r) : "v"(lo), "v"(hi)); return r; }
; #define LAS __attribute__((address_space(3)))
; __device__ __forceinline__ float fast_sigmoid(float v) { return __builtin_amdgcn_rcpf(1.0f + __expf(-v)); }
;     __device__ __forceinline__ void operator()(const f32x4 (&acc)[2][2][4][2], const Unit& u, int wr, int wc, int fr, int fq) const {
;     ...
;         { const LAS float* t_ = rs + ui * 256 + wr * 64 + fr;
; #pragma unroll
;           for (int ai = 0; ai < 2; ++ai)
; #pragma unroll
;               for (int m = 0; m < 4; ++m) sc[ai][m] = t_[ai * 128 + m * 16];
;           ++ui; }
; #pragma unroll
;         for (int ai = 0; ai < 2; ++ai)
; #pragma unroll
;             for (int m = 0; m < 4; ++m) {
;                 const int row = row0 + ai * 128 + m * 16; const float s = sc[ai][m];
;                 float a[8];
; #pragma unroll
;                 for (int n = 0; n < 2; ++n) { const f32x4 g = acc[ai][0][m][n] * s, up = acc[ai][1][m][n] * s;
; #pragma unroll
;                     for (int j = 0; j < 4; ++j) a[4 * n + j] = g[j] * fast_sigmoid(g[j]) * up[j]; }
;                 u32x4 w; w.x = cvt_pk_bf16(a[0], a[1]); w.y = cvt_pk_bf16(a[2], a[3]); w.z = cvt_pk_bf16(a[4], a[5]); w.w = cvt_pk_bf16(a[6], a[7]);
;                 *(u32x4*)(act + (size_t)row * FF + col0) = w;
;             }
.LBB0_1825:
	v_lshl_add_u32 v144, s49, 10, v152
	ds_read2_b32 v[158:159], v144 offset1:16
	ds_read2_b32 v[148:149], v144 offset0:32 offset1:48
	ds_read2_b32 v[146:147], v144 offset0:128 offset1:144
	ds_read2_b32 v[144:145], v144 offset0:160 offset1:176
	s_waitcnt lgkmcnt(0)
	v_mul_f32_e32 v124, v124, v158
	v_mul_f32_e32 v125, v125, v158
	v_mul_f32_e32 v126, v126, v158
	v_mul_f32_e32 v127, v127, v158
	v_mul_f32_e32 v116, v116, v158
	v_mul_f32_e32 v117, v117, v158
	v_mul_f32_e32 v118, v118, v158
	v_mul_f32_e32 v119, v119, v158
	v_mul_f32_e32 v120, v120, v158
	v_mul_f32_e32 v121, v121, v158
	v_mul_f32_e32 v122, v122, v158
	v_mul_f32_e32 v123, v123, v158
	v_mul_f32_e32 v112, v112, v158
	v_mul_f32_e32 v113, v113, v158
	v_mul_f32_e32 v114, v114, v158
	v_mul_f32_e32 v115, v115, v158
	v_mul_f32_e32 v166, 0xbfb8aa3b, v124
	v_mul_f32_e32 v167, 0xbfb8aa3b, v125
	v_mul_f32_e32 v170, 0xbfb8aa3b, v126
	v_mul_f32_e32 v171, 0xbfb8aa3b, v127
	v_mul_f32_e32 v172, 0xbfb8aa3b, v116
	v_mul_f32_e32 v173, 0xbfb8aa3b, v117
	v_mul_f32_e32 v174, 0xbfb8aa3b, v118
	v_mul_f32_e32 v175, 0xbfb8aa3b, v119
	v_exp_f32_e32 v166, v166
	v_exp_f32_e32 v167, v167
	v_exp_f32_e32 v170, v170
	v_exp_f32_e32 v171, v171
	v_exp_f32_e32 v172, v172
	v_exp_f32_e32 v173, v173
	v_exp_f32_e32 v174, v174
	v_exp_f32_e32 v175, v175
	v_add_f32_e32 v166, 1.0, v166
	v_add_f32_e32 v167, 1.0, v167
	v_add_f32_e32 v170, 1.0, v170
	v_add_f32_e32 v171, 1.0, v171
	v_add_f32_e32 v172, 1.0, v172
	v_add_f32_e32 v173, 1.0, v173
	v_add_f32_e32 v174, 1.0, v174
	v_add_f32_e32 v175, 1.0, v175
	v_rcp_f32_e32 v166, v166
	v_rcp_f32_e32 v167, v167
	v_rcp_f32_e32 v170, v170
	v_rcp_f32_e32 v171, v171
	v_rcp_f32_e32 v172, v172
	v_rcp_f32_e32 v173, v173
	v_rcp_f32_e32 v174, v174
	v_rcp_f32_e32 v175, v175
	v_mul_f32_e32 v124, v124, v166
	v_mul_f32_e32 v125, v125, v167
	v_mul_f32_e32 v126, v126, v170
	v_mul_f32_e32 v127, v127, v171
	v_mul_f32_e32 v116, v116, v172
	v_mul_f32_e32 v117, v117, v173
	v_mul_f32_e32 v118, v118, v174
	v_mul_f32_e32 v119, v119, v175
	v_mul_f32_e32 v166, v120, v124
	v_mul_f32_e32 v167, v121, v125
	v_mul_f32_e32 v170, v122, v126
	v_mul_f32_e32 v171, v123, v127
	v_mul_f32_e32 v172, v112, v116
	v_mul_f32_e32 v173, v113, v117
	v_mul_f32_e32 v174, v114, v118
	v_mul_f32_e32 v175, v115, v119
	v_cvt_pk_bf16_f32 v116, v166, v167
	v_cvt_pk_bf16_f32 v117, v170, v171
	v_cvt_pk_bf16_f32 v118, v172, v173
	v_cvt_pk_bf16_f32 v119, v174, v175
	v_lshl_or_b32 v164, s68, 7, v153
	v_lshl_add_u32 v157, s48, 8, v150
	v_ashrrev_i32_e32 v165, 31, v164
	s_mov_b64 s[48:49], -1
	s_andn2_b64 vcc, exec, s[44:45]
	v_mov_b64_e32 v[112:113], s[24:25]
	v_mad_i64_i32 v[120:121], s[6:7], v157, s61, v[112:113]
	v_lshlrev_b64 v[114:115], 1, v[164:165]
	v_lshl_add_u64 v[120:121], v[120:121], 0, v[114:115]
	global_store_dwordx4 v[120:121], v[116:119], off
	v_mul_f32_e32 v108, v108, v159
	v_mul_f32_e32 v109, v109, v159
	v_mul_f32_e32 v110, v110, v159
	v_mul_f32_e32 v111, v111, v159
	v_mul_f32_e32 v100, v100, v159
	v_mul_f32_e32 v101, v101, v159
	v_mul_f32_e32 v102, v102, v159
	v_mul_f32_e32 v103, v103, v159
	v_mul_f32_e32 v104, v104, v159
	v_mul_f32_e32 v105, v105, v159
	v_mul_f32_e32 v106, v106, v159
	v_mul_f32_e32 v107, v107, v159
	v_mul_f32_e32 v96, v96, v159
	v_mul_f32_e32 v97, v97, v159
	v_mul_f32_e32 v98, v98, v159
	v_mul_f32_e32 v99, v99, v159
	v_mul_f32_e32 v166, 0xbfb8aa3b, v108
	v_mul_f32_e32 v167, 0xbfb8aa3b, v109
	v_mul_f32_e32 v170, 0xbfb8aa3b, v110
	v_mul_f32_e32 v171, 0xbfb8aa3b, v111
	v_mul_f32_e32 v172, 0xbfb8aa3b, v100
	v_mul_f32_e32 v173, 0xbfb8aa3b, v101
	v_mul_f32_e32 v174, 0xbfb8aa3b, v102
	v_mul_f32_e32 v175, 0xbfb8aa3b, v103
	v_exp_f32_e32 v166, v166
	v_exp_f32_e32 v167, v167
	v_exp_f32_e32 v170, v170
	v_exp_f32_e32 v171, v171
	v_exp_f32_e32 v172, v172
	v_exp_f32_e32 v173, v173
	v_exp_f32_e32 v174, v174
	v_exp_f32_e32 v175, v175
	v_add_f32_e32 v166, 1.0, v166
	v_add_f32_e32 v167, 1.0, v167
	v_add_f32_e32 v170, 1.0, v170
	v_add_f32_e32 v171, 1.0, v171
	v_add_f32_e32 v172, 1.0, v172
	v_add_f32_e32 v173, 1.0, v173
	v_add_f32_e32 v174, 1.0, v174
	v_add_f32_e32 v175, 1.0, v175
	v_rcp_f32_e32 v166, v166
	v_rcp_f32_e32 v167, v167
	v_rcp_f32_e32 v170, v170
	v_rcp_f32_e32 v171, v171
	v_rcp_f32_e32 v172, v172
	v_rcp_f32_e32 v173, v173
	v_rcp_f32_e32 v174, v174
	v_rcp_f32_e32 v175, v175
	v_mul_f32_e32 v108, v108, v166
	v_mul_f32_e32 v109, v109, v167
	v_mul_f32_e32 v110, v110, v170
	v_mul_f32_e32 v111, v111, v171
	v_mul_f32_e32 v100, v100, v172
	v_mul_f32_e32 v101, v101, v173
	v_mul_f32_e32 v102, v102, v174
	v_mul_f32_e32 v103, v103, v175
	v_mul_f32_e32 v166, v104, v108
	v_mul_f32_e32 v167, v105, v109
	v_mul_f32_e32 v170, v106, v110
	v_mul_f32_e32 v171, v107, v111
	v_mul_f32_e32 v172, v96, v100
	v_mul_f32_e32 v173, v97, v101
	v_mul_f32_e32 v174, v98, v102
	v_mul_f32_e32 v175, v99, v103
	v_cvt_pk_bf16_f32 v96, v166, v167
	v_cvt_pk_bf16_f32 v97, v170, v171
	v_cvt_pk_bf16_f32 v98, v172, v173
	v_cvt_pk_bf16_f32 v99, v174, v175
	v_or_b32_e32 v102, 16, v157
	v_mad_i64_i32 v[100:101], s[6:7], v102, s61, v[112:113]
	v_lshl_add_u64 v[100:101], v[100:101], 0, v[114:115]
	global_store_dwordx4 v[100:101], v[96:99], off
	v_mul_f32_e32 v92, v92, v148
	v_mul_f32_e32 v93, v93, v148
	v_mul_f32_e32 v94, v94, v148
	v_mul_f32_e32 v95, v95, v148
	v_mul_f32_e32 v84, v84, v148
	v_mul_f32_e32 v85, v85, v148
	v_mul_f32_e32 v86, v86, v148
	v_mul_f32_e32 v87, v87, v148
	v_mul_f32_e32 v88, v88, v148
	v_mul_f32_e32 v89, v89, v148
	v_mul_f32_e32 v90, v90, v148
	v_mul_f32_e32 v91, v91, v148
	v_mul_f32_e32 v80, v80, v148
	v_mul_f32_e32 v81, v81, v148
	v_mul_f32_e32 v82, v82, v148
	v_mul_f32_e32 v83, v83, v148
	v_mul_f32_e32 v166, 0xbfb8aa3b, v92
; __device__ __forceinline__ unsigned cvt_pk_bf16(float lo, float hi) { unsigned r; asm volatile("v_cvt_pk_bf16_f32 %0, %1, %2" : "=v"(r) : "v"(lo), "v"(hi)); return r; }
; __device__ __forceinline__ float fast_sigmoid(float v) { return __builtin_amdgcn_rcpf(1.0f + __expf(-v)); }
;     __device__ __forceinline__ void operator()(const f32x4 (&acc)[2][2][4][2], const Unit& u, int wr, int wc, int fr, int fq) const {
;     ...
; #pragma unroll
;         for (int ai = 0; ai < 2; ++ai)
; #pragma unroll
;             for (int m = 0; m < 4; ++m) {
;                 const int row = row0 + ai * 128 + m * 16; const float s = sc[ai][m];
;                 float a[8];
; #pragma unroll
;                 for (int n = 0; n < 2; ++n) { const f32x4 g = acc[ai][0][m][n] * s, up = acc[ai][1][m][n] * s;
; #pragma unroll
;                     for (int j = 0; j < 4; ++j) a[4 * n + j] = g[j] * fast_sigmoid(g[j]) * up[j]; }
;                 u32x4 w; w.x = cvt_pk_bf16(a[0], a[1]); w.y = cvt_pk_bf16(a[2], a[3]); w.z = cvt_pk_bf16(a[4], a[5]); w.w = cvt_pk_bf16(a[6], a[7]);
;                 *(u32x4*)(act + (size_t)row * FF + col0) = w;
;             }
	v_mul_f32_e32 v167, 0xbfb8aa3b, v93
	v_mul_f32_e32 v170, 0xbfb8aa3b, v94
	v_mul_f32_e32 v171, 0xbfb8aa3b, v95
	v_mul_f32_e32 v172, 0xbfb8aa3b, v84
	v_mul_f32_e32 v173, 0xbfb8aa3b, v85
	v_mul_f32_e32 v174, 0xbfb8aa3b, v86
	v_mul_f32_e32 v175, 0xbfb8aa3b, v87
	v_exp_f32_e32 v166, v166
	v_exp_f32_e32 v167, v167
	v_exp_f32_e32 v170, v170
	v_exp_f32_e32 v171, v171
	v_exp_f32_e32 v172, v172
	v_exp_f32_e32 v173, v173
	v_exp_f32_e32 v174, v174
	v_exp_f32_e32 v175, v175
	v_add_f32_e32 v166, 1.0, v166
	v_add_f32_e32 v167, 1.0, v167
	v_add_f32_e32 v170, 1.0, v170
	v_add_f32_e32 v171, 1.0, v171
	v_add_f32_e32 v172, 1.0, v172
	v_add_f32_e32 v173, 1.0, v173
	v_add_f32_e32 v174, 1.0, v174
	v_add_f32_e32 v175, 1.0, v175
	v_rcp_f32_e32 v166, v166
	v_rcp_f32_e32 v167, v167
	v_rcp_f32_e32 v170, v170
	v_rcp_f32_e32 v171, v171
	v_rcp_f32_e32 v172, v172
	v_rcp_f32_e32 v173, v173
	v_rcp_f32_e32 v174, v174
	v_rcp_f32_e32 v175, v175
	v_mul_f32_e32 v92, v92, v166
	v_mul_f32_e32 v93, v93, v167
	v_mul_f32_e32 v94, v94, v170
	v_mul_f32_e32 v95, v95, v171
	v_mul_f32_e32 v84, v84, v172
	v_mul_f32_e32 v85, v85, v173
	v_mul_f32_e32 v86, v86, v174
	v_mul_f32_e32 v87, v87, v175
	v_mul_f32_e32 v166, v88, v92
	v_mul_f32_e32 v167, v89, v93
	v_mul_f32_e32 v170, v90, v94
	v_mul_f32_e32 v171, v91, v95
	v_mul_f32_e32 v172, v80, v84
	v_mul_f32_e32 v173, v81, v85
	v_mul_f32_e32 v174, v82, v86
	v_mul_f32_e32 v175, v83, v87
	v_cvt_pk_bf16_f32 v80, v166, v167
	v_cvt_pk_bf16_f32 v81, v170, v171
	v_cvt_pk_bf16_f32 v82, v172, v173
	v_cvt_pk_bf16_f32 v83, v174, v175
	v_or_b32_e32 v86, 32, v157
	v_mad_i64_i32 v[84:85], s[6:7], v86, s61, v[112:113]
	v_lshl_add_u64 v[84:85], v[84:85], 0, v[114:115]
	global_store_dwordx4 v[84:85], v[80:83], off
	v_mul_f32_e32 v76, v76, v149
	v_mul_f32_e32 v77, v77, v149
	v_mul_f32_e32 v78, v78, v149
	v_mul_f32_e32 v79, v79, v149
	v_mul_f32_e32 v68, v68, v149
	v_mul_f32_e32 v69, v69, v149
	v_mul_f32_e32 v70, v70, v149
	v_mul_f32_e32 v71, v71, v149
	v_mul_f32_e32 v72, v72, v149
	v_mul_f32_e32 v73, v73, v149
	v_mul_f32_e32 v74, v74, v149
	v_mul_f32_e32 v75, v75, v149
	v_mul_f32_e32 v64, v64, v149
	v_mul_f32_e32 v65, v65, v149
	v_mul_f32_e32 v66, v66, v149
	v_mul_f32_e32 v67, v67, v149
	v_mul_f32_e32 v166, 0xbfb8aa3b, v76
	v_mul_f32_e32 v167, 0xbfb8aa3b, v77
	v_mul_f32_e32 v170, 0xbfb8aa3b, v78
	v_mul_f32_e32 v171, 0xbfb8aa3b, v79
	v_mul_f32_e32 v172, 0xbfb8aa3b, v68
	v_mul_f32_e32 v173, 0xbfb8aa3b, v69
	v_mul_f32_e32 v174, 0xbfb8aa3b, v70
	v_mul_f32_e32 v175, 0xbfb8aa3b, v71
	v_exp_f32_e32 v166, v166
	v_exp_f32_e32 v167, v167
	v_exp_f32_e32 v170, v170
	v_exp_f32_e32 v171, v171
	v_exp_f32_e32 v172, v172
	v_exp_f32_e32 v173, v173
	v_exp_f32_e32 v174, v174
	v_exp_f32_e32 v175, v175
	v_add_f32_e32 v166, 1.0, v166
	v_add_f32_e32 v167, 1.0, v167
	v_add_f32_e32 v170, 1.0, v170
	v_add_f32_e32 v171, 1.0, v171
	v_add_f32_e32 v172, 1.0, v172
	v_add_f32_e32 v173, 1.0, v173
	v_add_f32_e32 v174, 1.0, v174
	v_add_f32_e32 v175, 1.0, v175
	v_rcp_f32_e32 v166, v166
	v_rcp_f32_e32 v167, v167
	v_rcp_f32_e32 v170, v170
	v_rcp_f32_e32 v171, v171
	v_rcp_f32_e32 v172, v172
	v_rcp_f32_e32 v173, v173
	v_rcp_f32_e32 v174, v174
	v_rcp_f32_e32 v175, v175
	v_mul_f32_e32 v76, v76, v166
	v_mul_f32_e32 v77, v77, v167
	v_mul_f32_e32 v78, v78, v170
	v_mul_f32_e32 v79, v79, v171
	v_mul_f32_e32 v68, v68, v172
	v_mul_f32_e32 v69, v69, v173
	v_mul_f32_e32 v70, v70, v174
	v_mul_f32_e32 v71, v71, v175
	v_mul_f32_e32 v166, v72, v76
	v_mul_f32_e32 v167, v73, v77
	v_mul_f32_e32 v170, v74, v78
	v_mul_f32_e32 v171, v75, v79
	v_mul_f32_e32 v172, v64, v68
	v_mul_f32_e32 v173, v65, v69
	v_mul_f32_e32 v174, v66, v70
	v_mul_f32_e32 v175, v67, v71
	v_cvt_pk_bf16_f32 v64, v166, v167
	v_cvt_pk_bf16_f32 v65, v170, v171
	v_cvt_pk_bf16_f32 v66, v172, v173
	v_cvt_pk_bf16_f32 v67, v174, v175
	v_or_b32_e32 v70, 48, v157
	v_mad_i64_i32 v[68:69], s[6:7], v70, s61, v[112:113]
	v_lshl_add_u64 v[68:69], v[68:69], 0, v[114:115]
	global_store_dwordx4 v[68:69], v[64:67], off
	v_mul_f32_e32 v60, v60, v146
	v_mul_f32_e32 v61, v61, v146
	v_mul_f32_e32 v62, v62, v146
	v_mul_f32_e32 v63, v63, v146
	v_mul_f32_e32 v52, v52, v146
	v_mul_f32_e32 v53, v53, v146
	v_mul_f32_e32 v54, v54, v146
	v_mul_f32_e32 v55, v55, v146
	v_mul_f32_e32 v56, v56, v146
	v_mul_f32_e32 v57, v57, v146
	v_mul_f32_e32 v58, v58, v146
	v_mul_f32_e32 v59, v59, v146
	v_mul_f32_e32 v48, v48, v146
	v_mul_f32_e32 v49, v49, v146
	v_mul_f32_e32 v50, v50, v146
	v_mul_f32_e32 v51, v51, v146
	v_mul_f32_e32 v166, 0xbfb8aa3b, v60
	v_mul_f32_e32 v167, 0xbfb8aa3b, v61
	v_mul_f32_e32 v170, 0xbfb8aa3b, v62
	v_mul_f32_e32 v171, 0xbfb8aa3b, v63
	v_mul_f32_e32 v172, 0xbfb8aa3b, v52
	v_mul_f32_e32 v173, 0xbfb8aa3b, v53
	v_mul_f32_e32 v174, 0xbfb8aa3b, v54
	v_mul_f32_e32 v175, 0xbfb8aa3b, v55
	v_exp_f32_e32 v166, v166
	v_exp_f32_e32 v167, v167
	v_exp_f32_e32 v170, v170
	v_exp_f32_e32 v171, v171
	v_exp_f32_e32 v172, v172
	v_exp_f32_e32 v173, v173
	v_exp_f32_e32 v174, v174
	v_exp_f32_e32 v175, v175
	v_add_f32_e32 v166, 1.0, v166
	v_add_f32_e32 v167, 1.0, v167
	v_add_f32_e32 v170, 1.0, v170
	v_add_f32_e32 v171, 1.0, v171
	v_add_f32_e32 v172, 1.0, v172
	v_add_f32_e32 v173, 1.0, v173
	v_add_f32_e32 v174, 1.0, v174
	v_add_f32_e32 v175, 1.0, v175
	v_rcp_f32_e32 v166, v166
	v_rcp_f32_e32 v167, v167
	v_rcp_f32_e32 v170, v170
	v_rcp_f32_e32 v171, v171
	v_rcp_f32_e32 v172, v172
	v_rcp_f32_e32 v173, v173
	v_rcp_f32_e32 v174, v174
	v_rcp_f32_e32 v175, v175
	v_mul_f32_e32 v60, v60, v166
	v_mul_f32_e32 v61, v61, v167
	v_mul_f32_e32 v62, v62, v170
	v_mul_f32_e32 v63, v63, v171
	v_mul_f32_e32 v52, v52, v172
	v_mul_f32_e32 v53, v53, v173
	v_mul_f32_e32 v54, v54, v174
	v_mul_f32_e32 v55, v55, v175
; __device__ __forceinline__ unsigned cvt_pk_bf16(float lo, float hi) { unsigned r; asm volatile("v_cvt_pk_bf16_f32 %0, %1, %2" : "=v"(r) : "v"(lo), "v"(hi)); return r; }
; __device__ __forceinline__ float fast_sigmoid(float v) { return __builtin_amdgcn_rcpf(1.0f + __expf(-v)); }
;     __device__ __forceinline__ void operator()(const f32x4 (&acc)[2][2][4][2], const Unit& u, int wr, int wc, int fr, int fq) const {
;     ...
; #pragma unroll
;         for (int ai = 0; ai < 2; ++ai)
; #pragma unroll
;             for (int m = 0; m < 4; ++m) {
;                 const int row = row0 + ai * 128 + m * 16; const float s = sc[ai][m];
;                 float a[8];
; #pragma unroll
;                 for (int n = 0; n < 2; ++n) { const f32x4 g = acc[ai][0][m][n] * s, up = acc[ai][1][m][n] * s;
; #pragma unroll
;                     for (int j = 0; j < 4; ++j) a[4 * n + j] = g[j] * fast_sigmoid(g[j]) * up[j]; }
;                 u32x4 w; w.x = cvt_pk_bf16(a[0], a[1]); w.y = cvt_pk_bf16(a[2], a[3]); w.z = cvt_pk_bf16(a[4], a[5]); w.w = cvt_pk_bf16(a[6], a[7]);
;                 *(u32x4*)(act + (size_t)row * FF + col0) = w;
;             }
	v_mul_f32_e32 v166, v56, v60
	v_mul_f32_e32 v167, v57, v61
	v_mul_f32_e32 v170, v58, v62
	v_mul_f32_e32 v171, v59, v63
	v_mul_f32_e32 v172, v48, v52
	v_mul_f32_e32 v173, v49, v53
	v_mul_f32_e32 v174, v50, v54
	v_mul_f32_e32 v175, v51, v55
	v_cvt_pk_bf16_f32 v48, v166, v167
	v_cvt_pk_bf16_f32 v49, v170, v171
	v_cvt_pk_bf16_f32 v50, v172, v173
	v_cvt_pk_bf16_f32 v51, v174, v175
	v_add_u32_e32 v66, 0x80, v157
	v_mad_i64_i32 v[52:53], s[6:7], v66, s61, v[112:113]
	v_lshl_add_u64 v[52:53], v[52:53], 0, v[114:115]
	global_store_dwordx4 v[52:53], v[48:51], off
	v_mul_f32_e32 v44, v44, v147
	v_mul_f32_e32 v45, v45, v147
	v_mul_f32_e32 v46, v46, v147
	v_mul_f32_e32 v47, v47, v147
	v_mul_f32_e32 v36, v36, v147
	v_mul_f32_e32 v37, v37, v147
	v_mul_f32_e32 v38, v38, v147
	v_mul_f32_e32 v39, v39, v147
	v_mul_f32_e32 v40, v40, v147
	v_mul_f32_e32 v41, v41, v147
	v_mul_f32_e32 v42, v42, v147
	v_mul_f32_e32 v43, v43, v147
	v_mul_f32_e32 v32, v32, v147
	v_mul_f32_e32 v33, v33, v147
	v_mul_f32_e32 v34, v34, v147
	v_mul_f32_e32 v35, v35, v147
	v_mul_f32_e32 v166, 0xbfb8aa3b, v44
	v_mul_f32_e32 v167, 0xbfb8aa3b, v45
	v_mul_f32_e32 v170, 0xbfb8aa3b, v46
	v_mul_f32_e32 v171, 0xbfb8aa3b, v47
	v_mul_f32_e32 v172, 0xbfb8aa3b, v36
	v_mul_f32_e32 v173, 0xbfb8aa3b, v37
	v_mul_f32_e32 v174, 0xbfb8aa3b, v38
	v_mul_f32_e32 v175, 0xbfb8aa3b, v39
	v_exp_f32_e32 v166, v166
	v_exp_f32_e32 v167, v167
	v_exp_f32_e32 v170, v170
	v_exp_f32_e32 v171, v171
	v_exp_f32_e32 v172, v172
	v_exp_f32_e32 v173, v173
	v_exp_f32_e32 v174, v174
	v_exp_f32_e32 v175, v175
	v_add_f32_e32 v166, 1.0, v166
	v_add_f32_e32 v167, 1.0, v167
	v_add_f32_e32 v170, 1.0, v170
	v_add_f32_e32 v171, 1.0, v171
	v_add_f32_e32 v172, 1.0, v172
	v_add_f32_e32 v173, 1.0, v173
	v_add_f32_e32 v174, 1.0, v174
	v_add_f32_e32 v175, 1.0, v175
	v_rcp_f32_e32 v166, v166
	v_rcp_f32_e32 v167, v167
	v_rcp_f32_e32 v170, v170
	v_rcp_f32_e32 v171, v171
	v_rcp_f32_e32 v172, v172
	v_rcp_f32_e32 v173, v173
	v_rcp_f32_e32 v174, v174
	v_rcp_f32_e32 v175, v175
	v_mul_f32_e32 v44, v44, v166
	v_mul_f32_e32 v45, v45, v167
	v_mul_f32_e32 v46, v46, v170
	v_mul_f32_e32 v47, v47, v171
	v_mul_f32_e32 v36, v36, v172
	v_mul_f32_e32 v37, v37, v173
	v_mul_f32_e32 v38, v38, v174
	v_mul_f32_e32 v39, v39, v175
	v_mul_f32_e32 v166, v40, v44
	v_mul_f32_e32 v167, v41, v45
	v_mul_f32_e32 v170, v42, v46
	v_mul_f32_e32 v171, v43, v47
	v_mul_f32_e32 v172, v32, v36
	v_mul_f32_e32 v173, v33, v37
	v_mul_f32_e32 v174, v34, v38
	v_mul_f32_e32 v175, v35, v39
	v_cvt_pk_bf16_f32 v32, v166, v167
	v_cvt_pk_bf16_f32 v33, v170, v171
	v_cvt_pk_bf16_f32 v34, v172, v173
	v_cvt_pk_bf16_f32 v35, v174, v175
	v_add_u32_e32 v38, 0x90, v157
	v_mad_i64_i32 v[36:37], s[6:7], v38, s61, v[112:113]
	v_lshl_add_u64 v[36:37], v[36:37], 0, v[114:115]
	global_store_dwordx4 v[36:37], v[32:35], off
	v_mul_f32_e32 v28, v28, v144
	v_mul_f32_e32 v29, v29, v144
	v_mul_f32_e32 v30, v30, v144
	v_mul_f32_e32 v31, v31, v144
	v_mul_f32_e32 v20, v20, v144
	v_mul_f32_e32 v21, v21, v144
	v_mul_f32_e32 v22, v22, v144
	v_mul_f32_e32 v23, v23, v144
	v_mul_f32_e32 v24, v24, v144
	v_mul_f32_e32 v25, v25, v144
	v_mul_f32_e32 v26, v26, v144
	v_mul_f32_e32 v27, v27, v144
	v_mul_f32_e32 v16, v16, v144
	v_mul_f32_e32 v17, v17, v144
	v_mul_f32_e32 v18, v18, v144
	v_mul_f32_e32 v19, v19, v144
	v_mul_f32_e32 v166, 0xbfb8aa3b, v28
	v_mul_f32_e32 v167, 0xbfb8aa3b, v29
	v_mul_f32_e32 v170, 0xbfb8aa3b, v30
	v_mul_f32_e32 v171, 0xbfb8aa3b, v31
	v_mul_f32_e32 v172, 0xbfb8aa3b, v20
	v_mul_f32_e32 v173, 0xbfb8aa3b, v21
	v_mul_f32_e32 v174, 0xbfb8aa3b, v22
	v_mul_f32_e32 v175, 0xbfb8aa3b, v23
	v_exp_f32_e32 v166, v166
	v_exp_f32_e32 v167, v167
	v_exp_f32_e32 v170, v170
	v_exp_f32_e32 v171, v171
; __device__ __forceinline__ unsigned cvt_pk_bf16(float lo, float hi) { unsigned r; asm volatile("v_cvt_pk_bf16_f32 %0, %1, %2" : "=v"(r) : "v"(lo), "v"(hi)); return r; }
; __device__ __forceinline__ float fast_sigmoid(float v) { return __builtin_amdgcn_rcpf(1.0f + __expf(-v)); }
;     __device__ __forceinline__ void operator()(const f32x4 (&acc)[2][2][4][2], const Unit& u, int wr, int wc, int fr, int fq) const {
;     ...
; #pragma unroll
;         for (int ai = 0; ai < 2; ++ai)
; #pragma unroll
;             for (int m = 0; m < 4; ++m) {
;                 const int row = row0 + ai * 128 + m * 16; const float s = sc[ai][m];
;                 float a[8];
; #pragma unroll
;                 for (int n = 0; n < 2; ++n) { const f32x4 g = acc[ai][0][m][n] * s, up = acc[ai][1][m][n] * s;
; #pragma unroll
;                     for (int j = 0; j < 4; ++j) a[4 * n + j] = g[j] * fast_sigmoid(g[j]) * up[j]; }
;                 u32x4 w; w.x = cvt_pk_bf16(a[0], a[1]); w.y = cvt_pk_bf16(a[2], a[3]); w.z = cvt_pk_bf16(a[4], a[5]); w.w = cvt_pk_bf16(a[6], a[7]);
;                 *(u32x4*)(act + (size_t)row * FF + col0) = w;
;             }
	v_exp_f32_e32 v172, v172
	v_exp_f32_e32 v173, v173
	v_exp_f32_e32 v174, v174
	v_exp_f32_e32 v175, v175
	v_add_f32_e32 v166, 1.0, v166
	v_add_f32_e32 v167, 1.0, v167
	v_add_f32_e32 v170, 1.0, v170
	v_add_f32_e32 v171, 1.0, v171
	v_add_f32_e32 v172, 1.0, v172
	v_add_f32_e32 v173, 1.0, v173
	v_add_f32_e32 v174, 1.0, v174
	v_add_f32_e32 v175, 1.0, v175
	v_rcp_f32_e32 v166, v166
	v_rcp_f32_e32 v167, v167
	v_rcp_f32_e32 v170, v170
	v_rcp_f32_e32 v171, v171
	v_rcp_f32_e32 v172, v172
	v_rcp_f32_e32 v173, v173
	v_rcp_f32_e32 v174, v174
	v_rcp_f32_e32 v175, v175
	v_mul_f32_e32 v28, v28, v166
	v_mul_f32_e32 v29, v29, v167
	v_mul_f32_e32 v30, v30, v170
	v_mul_f32_e32 v31, v31, v171
	v_mul_f32_e32 v20, v20, v172
	v_mul_f32_e32 v21, v21, v173
	v_mul_f32_e32 v22, v22, v174
	v_mul_f32_e32 v23, v23, v175
	v_mul_f32_e32 v166, v24, v28
	v_mul_f32_e32 v167, v25, v29
	v_mul_f32_e32 v170, v26, v30
	v_mul_f32_e32 v171, v27, v31
	v_mul_f32_e32 v172, v16, v20
	v_mul_f32_e32 v173, v17, v21
	v_mul_f32_e32 v174, v18, v22
	v_mul_f32_e32 v175, v19, v23
	v_cvt_pk_bf16_f32 v16, v166, v167
	v_cvt_pk_bf16_f32 v17, v170, v171
	v_cvt_pk_bf16_f32 v18, v172, v173
	v_cvt_pk_bf16_f32 v19, v174, v175
	v_add_u32_e32 v22, 0xa0, v157
	v_mad_i64_i32 v[20:21], s[6:7], v22, s61, v[112:113]
	v_lshl_add_u64 v[20:21], v[20:21], 0, v[114:115]
	global_store_dwordx4 v[20:21], v[16:19], off
	v_mul_f32_e32 v12, v12, v145
	v_mul_f32_e32 v13, v13, v145
	v_mul_f32_e32 v14, v14, v145
	v_mul_f32_e32 v15, v15, v145
	v_mul_f32_e32 v4, v4, v145
	v_mul_f32_e32 v5, v5, v145
	v_mul_f32_e32 v6, v6, v145
	v_mul_f32_e32 v7, v7, v145
	v_mul_f32_e32 v8, v8, v145
	v_mul_f32_e32 v9, v9, v145
	v_mul_f32_e32 v10, v10, v145
	v_mul_f32_e32 v11, v11, v145
	v_mul_f32_e32 v0, v0, v145
	v_mul_f32_e32 v1, v1, v145
	v_mul_f32_e32 v2, v2, v145
	v_mul_f32_e32 v3, v3, v145
	v_mul_f32_e32 v166, 0xbfb8aa3b, v12
	v_mul_f32_e32 v167, 0xbfb8aa3b, v13
	v_mul_f32_e32 v170, 0xbfb8aa3b, v14
	v_mul_f32_e32 v171, 0xbfb8aa3b, v15
	v_mul_f32_e32 v172, 0xbfb8aa3b, v4
	v_mul_f32_e32 v173, 0xbfb8aa3b, v5
	v_mul_f32_e32 v174, 0xbfb8aa3b, v6
	v_mul_f32_e32 v175, 0xbfb8aa3b, v7
	v_exp_f32_e32 v166, v166
	v_exp_f32_e32 v167, v167
	v_exp_f32_e32 v170, v170
	v_exp_f32_e32 v171, v171
	v_exp_f32_e32 v172, v172
	v_exp_f32_e32 v173, v173
	v_exp_f32_e32 v174, v174
	v_exp_f32_e32 v175, v175
	v_add_f32_e32 v166, 1.0, v166
	v_add_f32_e32 v167, 1.0, v167
	v_add_f32_e32 v170, 1.0, v170
	v_add_f32_e32 v171, 1.0, v171
	v_add_f32_e32 v172, 1.0, v172
	v_add_f32_e32 v173, 1.0, v173
	v_add_f32_e32 v174, 1.0, v174
	v_add_f32_e32 v175, 1.0, v175
	v_rcp_f32_e32 v166, v166
	v_rcp_f32_e32 v167, v167
	v_rcp_f32_e32 v170, v170
	v_rcp_f32_e32 v171, v171
	v_rcp_f32_e32 v172, v172
	v_rcp_f32_e32 v173, v173
	v_rcp_f32_e32 v174, v174
	v_rcp_f32_e32 v175, v175
	v_mul_f32_e32 v12, v12, v166
	v_mul_f32_e32 v13, v13, v167
	v_mul_f32_e32 v14, v14, v170
	v_mul_f32_e32 v15, v15, v171
	v_mul_f32_e32 v4, v4, v172
	v_mul_f32_e32 v5, v5, v173
	v_mul_f32_e32 v6, v6, v174
	v_mul_f32_e32 v7, v7, v175
	v_mul_f32_e32 v166, v8, v12
	v_mul_f32_e32 v167, v9, v13
	v_mul_f32_e32 v170, v10, v14
	v_mul_f32_e32 v171, v11, v15
	v_mul_f32_e32 v172, v0, v4
	v_mul_f32_e32 v173, v1, v5
	v_mul_f32_e32 v174, v2, v6
	v_mul_f32_e32 v175, v3, v7
	v_cvt_pk_bf16_f32 v0, v166, v167
	v_cvt_pk_bf16_f32 v1, v170, v171
	v_cvt_pk_bf16_f32 v2, v172, v173
	v_cvt_pk_bf16_f32 v3, v174, v175
	v_add_u32_e32 v6, 0xb0, v157
	v_mad_i64_i32 v[4:5], s[6:7], v6, s61, v[112:113]
	v_lshl_add_u64 v[4:5], v[4:5], 0, v[114:115]
	global_store_dwordx4 v[4:5], v[0:3], off
	s_cbranch_vccnz .LBB0_1814
	s_andn2_b64 vcc, exec, s[28:29]
	s_cbranch_vccnz .LBB0_1813
	s_barrier
	s_branch .LBB0_1813
